# hand-scheduled unrolled scan step loops (4 mixers, paired path)
# speedup vs baseline: 1.0631x; 1.0631x over previous
; template <int KG> __device__ __forceinline__ float redKG(float x) { x = red8d(x); if (KG == 16) x += dpp_rm(x); return x; }
; template <int MIX, int KPL, int KG>
; __device__ __forceinline__ float do_step(const StepIn<MIX, KPL>& s, float (&S)[KPL], const float gam) {
;     ...
;   } else {
;     float o0 = 0.f, o1 = 0.f;
; #pragma unroll
;     for (int i = 0; i < KPL; i += 2) {
;       const float d0 = (MIX == 3) ? gam : s.d[i], d1 = (MIX == 3) ? gam : s.d[i + 1];
;       S[i] = d0 * S[i] + s.k[i] * s.v; S[i + 1] = d1 * S[i + 1] + s.k[i + 1] * s.v;
;       o0 += s.q[i] * S[i]; o1 += s.q[i + 1] * S[i + 1];
;     }
;     return redKG<KG>(o0 + o1);
;   }
; template <int MIX>
; __device__ __forceinline__ void scan_part(const Params& p, const int layer, const int smp, const int b0, const int bstep, const int bend, const int h, const int part, char* lds, const int tid) {
;     ...
;     {
;       StepIn<MIX, KPL> sa, sb;
;       float osave = 0.f;
;       load_step<MIX, KPL>(qkdv, scal, 0, kg, col, sa);
;       for (int t = 0; t < ntok; t += 2) {
;         load_step<MIX, KPL>(qkdv, scal, t + 1, kg, col, sb);
;         __builtin_amdgcn_sched_barrier(0);
;         const float oa = do_step<MIX, KPL, KG>(sa, S, gam);
;         osave = (kg == (t & (KG - 1))) ? oa : osave;
;         load_step<MIX, KPL>(qkdv, scal, min(t + 2, ntok - 1), kg, col, sa);
;         __builtin_amdgcn_sched_barrier(0);
;         const float ob = do_step<MIX, KPL, KG>(sb, S, gam);
;         osave = (kg == ((t + 1) & (KG - 1))) ? ob : osave;
;         if (((t + 2) & (KG - 1)) == 0) obuf[(t + 2 - KG + kg) * CW + col] = osave;
;       }
;       const int remn = ntok & (KG - 1);
;       if (remn != 0 && kg < remn) obuf[(ntok - remn + kg) * CW + col] = osave;
;     }
.LBB0_320:
	v_mov_b32_e32 v210, v28
	v_mov_b32_e32 v211, v59
	v_and_b32_e32 v212, 4, v57
	s_lshr_b32 s43, s44, 4
	v_lshl_add_u32 v212, v212, 5, v59
	ds_read_b128 v[138:141], v210 offset:256
	ds_read_b128 v[142:145], v210 offset:272
	ds_read_b32 v102, v211 offset:768
	ds_read_b128 v[68:71], v210
	ds_read_b128 v[72:75], v210 offset:16
	ds_read_b128 v[148:151], v210 offset:1280
	ds_read_b128 v[152:155], v210 offset:1296
	ds_read_b32 v104, v211 offset:1792
	ds_read_b128 v[76:79], v210 offset:1024
	ds_read_b128 v[80:83], v210 offset:1040
.Lscan3p_blk:
	s_waitcnt lgkmcnt(5)
	ds_read_b128 v[174:177], v210 offset:2304
	ds_read_b32 v106, v211 offset:2816
	ds_read_b128 v[178:181], v210 offset:2320
	ds_read_b128 v[84:87], v210 offset:2048
	ds_read_b128 v[184:187], v210 offset:3328
	ds_read_b32 v132, v211 offset:3840
	ds_read_b128 v[88:91], v210 offset:2064
	v_pk_mul_f32 v[134:135], v[138:139], v[102:103] op_sel_hi:[1,0]
	v_pk_mul_f32 v[158:159], v[140:141], v[102:103] op_sel_hi:[1,0]
	v_pk_fma_f32 v[30:31], v[30:31], v[44:45], v[134:135]
	ds_read_b128 v[188:191], v210 offset:3344
	ds_read_b128 v[94:97], v210 offset:3072
	v_pk_mul_f32 v[168:169], v[142:143], v[102:103] op_sel_hi:[1,0]
	v_pk_fma_f32 v[50:51], v[50:51], v[44:45], v[158:159]
	v_pk_mul_f32 v[202:203], v[68:69], v[30:31]
	v_pk_mul_f32 v[192:193], v[144:145], v[102:103] op_sel_hi:[1,0]
	v_pk_fma_f32 v[52:53], v[52:53], v[44:45], v[168:169]
	v_pk_fma_f32 v[202:203], v[70:71], v[50:51], v[202:203]
	ds_read_b128 v[98:101], v210 offset:3088
	s_waitcnt lgkmcnt(3)
	v_pk_mul_f32 v[194:195], v[148:149], v[104:105] op_sel_hi:[1,0]
	v_pk_fma_f32 v[54:55], v[54:55], v[44:45], v[192:193]
	v_pk_fma_f32 v[202:203], v[72:73], v[52:53], v[202:203]
	v_pk_mul_f32 v[196:197], v[150:151], v[104:105] op_sel_hi:[1,0]
	v_pk_fma_f32 v[30:31], v[30:31], v[44:45], v[194:195]
	v_pk_fma_f32 v[202:203], v[74:75], v[54:55], v[202:203]
	v_pk_mul_f32 v[198:199], v[152:153], v[104:105] op_sel_hi:[1,0]
	v_pk_fma_f32 v[50:51], v[50:51], v[44:45], v[196:197]
	v_pk_mul_f32 v[204:205], v[76:77], v[30:31]
	v_add_f32_e32 v67, v202, v203
	v_pk_mul_f32 v[200:201], v[154:155], v[104:105] op_sel_hi:[1,0]
	v_pk_fma_f32 v[52:53], v[52:53], v[44:45], v[198:199]
	v_pk_fma_f32 v[204:205], v[78:79], v[50:51], v[204:205]
	ds_read_b128 v[138:141], v210 offset:4352
	ds_read_b32 v102, v211 offset:4864
	v_pk_fma_f32 v[54:55], v[54:55], v[44:45], v[200:201]
	v_pk_fma_f32 v[204:205], v[80:81], v[52:53], v[204:205]
	v_pk_fma_f32 v[204:205], v[82:83], v[54:55], v[204:205]
	ds_read_b128 v[142:145], v210 offset:4368
	ds_read_b128 v[68:71], v210 offset:4096
	v_add_f32_dpp v67, v67, v67 quad_perm:[1,0,3,2] row_mask:0xf bank_mask:0xf bound_ctrl:1
	v_add_f32_e32 v92, v204, v205
	ds_read_b128 v[148:151], v210 offset:5376
	ds_read_b32 v104, v211 offset:5888
	ds_read_b128 v[72:75], v210 offset:4112
	v_pk_mul_f32 v[134:135], v[174:175], v[106:107] op_sel_hi:[1,0]
	v_pk_mul_f32 v[158:159], v[176:177], v[106:107] op_sel_hi:[1,0]
	v_pk_fma_f32 v[30:31], v[30:31], v[44:45], v[134:135]
	ds_read_b128 v[152:155], v210 offset:5392
	ds_read_b128 v[76:79], v210 offset:5120
	v_add_f32_dpp v67, v67, v67 quad_perm:[2,3,0,1] row_mask:0xf bank_mask:0xf bound_ctrl:1
	v_add_f32_dpp v92, v92, v92 quad_perm:[1,0,3,2] row_mask:0xf bank_mask:0xf bound_ctrl:1
	v_pk_mul_f32 v[168:169], v[178:179], v[106:107] op_sel_hi:[1,0]
	v_pk_fma_f32 v[50:51], v[50:51], v[44:45], v[158:159]
	v_pk_mul_f32 v[202:203], v[84:85], v[30:31]
	v_pk_mul_f32 v[192:193], v[180:181], v[106:107] op_sel_hi:[1,0]
	v_pk_fma_f32 v[52:53], v[52:53], v[44:45], v[168:169]
	v_pk_fma_f32 v[202:203], v[86:87], v[50:51], v[202:203]
	ds_read_b128 v[80:83], v210 offset:5136
	v_pk_mul_f32 v[194:195], v[184:185], v[132:133] op_sel_hi:[1,0]
	v_pk_fma_f32 v[54:55], v[54:55], v[44:45], v[192:193]
	v_pk_fma_f32 v[202:203], v[88:89], v[52:53], v[202:203]
	v_pk_mul_f32 v[196:197], v[186:187], v[132:133] op_sel_hi:[1,0]
	v_pk_fma_f32 v[30:31], v[30:31], v[44:45], v[194:195]
	v_add_f32_dpp v131, v67, v67 row_half_mirror row_mask:0xf bank_mask:0x5
	v_add_f32_dpp v92, v92, v92 quad_perm:[2,3,0,1] row_mask:0xf bank_mask:0xf bound_ctrl:1
	v_pk_fma_f32 v[202:203], v[90:91], v[54:55], v[202:203]
	s_waitcnt lgkmcnt(1)
	v_pk_mul_f32 v[198:199], v[188:189], v[132:133] op_sel_hi:[1,0]
	v_pk_fma_f32 v[50:51], v[50:51], v[44:45], v[196:197]
	v_pk_mul_f32 v[204:205], v[94:95], v[30:31]
	v_add_f32_e32 v67, v202, v203
	v_pk_mul_f32 v[200:201], v[190:191], v[132:133] op_sel_hi:[1,0]
	v_pk_fma_f32 v[52:53], v[52:53], v[44:45], v[198:199]
	v_pk_fma_f32 v[204:205], v[96:97], v[50:51], v[204:205]
	ds_read_b128 v[174:177], v210 offset:6400
	ds_read_b32 v106, v211 offset:6912
	v_pk_fma_f32 v[54:55], v[54:55], v[44:45], v[200:201]
	v_pk_fma_f32 v[204:205], v[98:99], v[52:53], v[204:205]
	v_add_f32_dpp v131, v92, v92 row_half_mirror row_mask:0xf bank_mask:0xa
	v_pk_fma_f32 v[204:205], v[100:101], v[54:55], v[204:205]
	ds_read_b128 v[178:181], v210 offset:6416
	ds_read_b128 v[84:87], v210 offset:6144
	v_add_f32_dpp v67, v67, v67 quad_perm:[1,0,3,2] row_mask:0xf bank_mask:0xf bound_ctrl:1
	v_add_f32_e32 v92, v204, v205
	ds_read_b128 v[184:187], v210 offset:7424
	ds_read_b32 v132, v211 offset:7936
	ds_read_b128 v[88:91], v210 offset:6160
	v_pk_mul_f32 v[134:135], v[138:139], v[102:103] op_sel_hi:[1,0]
	v_pk_mul_f32 v[158:159], v[140:141], v[102:103] op_sel_hi:[1,0]
	v_pk_fma_f32 v[30:31], v[30:31], v[44:45], v[134:135]
	ds_read_b128 v[188:191], v210 offset:7440
	ds_read_b128 v[94:97], v210 offset:7168
	v_add_f32_dpp v67, v67, v67 quad_perm:[2,3,0,1] row_mask:0xf bank_mask:0xf bound_ctrl:1
	v_add_f32_dpp v92, v92, v92 quad_perm:[1,0,3,2] row_mask:0xf bank_mask:0xf bound_ctrl:1
; template <int KG> __device__ __forceinline__ float redKG(float x) { x = red8d(x); if (KG == 16) x += dpp_rm(x); return x; }
; template <int MIX, int KPL, int KG>
; __device__ __forceinline__ float do_step(const StepIn<MIX, KPL>& s, float (&S)[KPL], const float gam) {
;     ...
;   } else {
;     float o0 = 0.f, o1 = 0.f;
; #pragma unroll
;     for (int i = 0; i < KPL; i += 2) {
;       const float d0 = (MIX == 3) ? gam : s.d[i], d1 = (MIX == 3) ? gam : s.d[i + 1];
;       S[i] = d0 * S[i] + s.k[i] * s.v; S[i + 1] = d1 * S[i + 1] + s.k[i + 1] * s.v;
;       o0 += s.q[i] * S[i]; o1 += s.q[i + 1] * S[i + 1];
;     }
;     return redKG<KG>(o0 + o1);
;   }
; template <int MIX>
; __device__ __forceinline__ void scan_part(const Params& p, const int layer, const int smp, const int b0, const int bstep, const int bend, const int h, const int part, char* lds, const int tid) {
;     ...
;     {
;       StepIn<MIX, KPL> sa, sb;
;       float osave = 0.f;
;       load_step<MIX, KPL>(qkdv, scal, 0, kg, col, sa);
;       for (int t = 0; t < ntok; t += 2) {
;         load_step<MIX, KPL>(qkdv, scal, t + 1, kg, col, sb);
;         __builtin_amdgcn_sched_barrier(0);
;         const float oa = do_step<MIX, KPL, KG>(sa, S, gam);
;         osave = (kg == (t & (KG - 1))) ? oa : osave;
;         load_step<MIX, KPL>(qkdv, scal, min(t + 2, ntok - 1), kg, col, sa);
;         __builtin_amdgcn_sched_barrier(0);
;         const float ob = do_step<MIX, KPL, KG>(sb, S, gam);
;         osave = (kg == ((t + 1) & (KG - 1))) ? ob : osave;
;         if (((t + 2) & (KG - 1)) == 0) obuf[(t + 2 - KG + kg) * CW + col] = osave;
;       }
;       const int remn = ntok & (KG - 1);
;       if (remn != 0 && kg < remn) obuf[(ntok - remn + kg) * CW + col] = osave;
;     }
	v_pk_mul_f32 v[168:169], v[142:143], v[102:103] op_sel_hi:[1,0]
	v_pk_fma_f32 v[50:51], v[50:51], v[44:45], v[158:159]
	v_pk_mul_f32 v[202:203], v[68:69], v[30:31]
	v_pk_mul_f32 v[192:193], v[144:145], v[102:103] op_sel_hi:[1,0]
	v_pk_fma_f32 v[52:53], v[52:53], v[44:45], v[168:169]
	v_pk_fma_f32 v[202:203], v[70:71], v[50:51], v[202:203]
	ds_read_b128 v[98:101], v210 offset:7184
	v_pk_mul_f32 v[194:195], v[148:149], v[104:105] op_sel_hi:[1,0]
	v_pk_fma_f32 v[54:55], v[54:55], v[44:45], v[192:193]
	v_pk_fma_f32 v[202:203], v[72:73], v[52:53], v[202:203]
	v_pk_mul_f32 v[196:197], v[150:151], v[104:105] op_sel_hi:[1,0]
	v_pk_fma_f32 v[30:31], v[30:31], v[44:45], v[194:195]
	v_add_f32_dpp v136, v67, v67 row_half_mirror row_mask:0xf bank_mask:0x5
	v_add_f32_dpp v92, v92, v92 quad_perm:[2,3,0,1] row_mask:0xf bank_mask:0xf bound_ctrl:1
	v_pk_fma_f32 v[202:203], v[74:75], v[54:55], v[202:203]
	v_pk_mul_f32 v[198:199], v[152:153], v[104:105] op_sel_hi:[1,0]
	v_pk_fma_f32 v[50:51], v[50:51], v[44:45], v[196:197]
	v_pk_mul_f32 v[204:205], v[76:77], v[30:31]
	v_add_f32_e32 v67, v202, v203
	v_pk_mul_f32 v[200:201], v[154:155], v[104:105] op_sel_hi:[1,0]
	v_pk_fma_f32 v[52:53], v[52:53], v[44:45], v[198:199]
	v_pk_fma_f32 v[204:205], v[78:79], v[50:51], v[204:205]
	ds_read_b128 v[138:141], v210 offset:8448
	ds_read_b32 v102, v211 offset:8960
	v_pk_fma_f32 v[54:55], v[54:55], v[44:45], v[200:201]
	s_waitcnt lgkmcnt(2)
	v_pk_fma_f32 v[204:205], v[80:81], v[52:53], v[204:205]
	v_add_f32_dpp v136, v92, v92 row_half_mirror row_mask:0xf bank_mask:0xa
	v_pk_fma_f32 v[204:205], v[82:83], v[54:55], v[204:205]
	ds_read_b128 v[142:145], v210 offset:8464
	ds_read_b128 v[68:71], v210 offset:8192
	v_add_f32_dpp v67, v67, v67 quad_perm:[1,0,3,2] row_mask:0xf bank_mask:0xf bound_ctrl:1
	v_add_f32_e32 v92, v204, v205
	ds_read_b128 v[148:151], v210 offset:9472
	ds_read_b32 v104, v211 offset:9984
	ds_read_b128 v[72:75], v210 offset:8208
	v_pk_mul_f32 v[134:135], v[174:175], v[106:107] op_sel_hi:[1,0]
	v_pk_mul_f32 v[158:159], v[176:177], v[106:107] op_sel_hi:[1,0]
	v_pk_fma_f32 v[30:31], v[30:31], v[44:45], v[134:135]
	ds_read_b128 v[152:155], v210 offset:9488
	ds_read_b128 v[76:79], v210 offset:9216
	v_add_f32_dpp v67, v67, v67 quad_perm:[2,3,0,1] row_mask:0xf bank_mask:0xf bound_ctrl:1
	v_add_f32_dpp v92, v92, v92 quad_perm:[1,0,3,2] row_mask:0xf bank_mask:0xf bound_ctrl:1
	v_pk_mul_f32 v[168:169], v[178:179], v[106:107] op_sel_hi:[1,0]
	v_pk_fma_f32 v[50:51], v[50:51], v[44:45], v[158:159]
	v_pk_mul_f32 v[202:203], v[84:85], v[30:31]
	v_pk_mul_f32 v[192:193], v[180:181], v[106:107] op_sel_hi:[1,0]
	v_pk_fma_f32 v[52:53], v[52:53], v[44:45], v[168:169]
	v_pk_fma_f32 v[202:203], v[86:87], v[50:51], v[202:203]
	ds_read_b128 v[80:83], v210 offset:9232
	v_pk_mul_f32 v[194:195], v[184:185], v[132:133] op_sel_hi:[1,0]
	v_pk_fma_f32 v[54:55], v[54:55], v[44:45], v[192:193]
	v_pk_fma_f32 v[202:203], v[88:89], v[52:53], v[202:203]
	v_pk_mul_f32 v[196:197], v[186:187], v[132:133] op_sel_hi:[1,0]
	v_pk_fma_f32 v[30:31], v[30:31], v[44:45], v[194:195]
	v_add_f32_dpp v146, v67, v67 row_half_mirror row_mask:0xf bank_mask:0x5
	v_add_f32_dpp v92, v92, v92 quad_perm:[2,3,0,1] row_mask:0xf bank_mask:0xf bound_ctrl:1
	v_pk_fma_f32 v[202:203], v[90:91], v[54:55], v[202:203]
	v_pk_mul_f32 v[198:199], v[188:189], v[132:133] op_sel_hi:[1,0]
	v_pk_fma_f32 v[50:51], v[50:51], v[44:45], v[196:197]
	v_pk_mul_f32 v[204:205], v[94:95], v[30:31]
	v_add_f32_e32 v67, v202, v203
	v_pk_mul_f32 v[200:201], v[190:191], v[132:133] op_sel_hi:[1,0]
	v_pk_fma_f32 v[52:53], v[52:53], v[44:45], v[198:199]
	v_pk_fma_f32 v[204:205], v[96:97], v[50:51], v[204:205]
	ds_read_b128 v[174:177], v210 offset:10496
	ds_read_b32 v106, v211 offset:11008
	v_pk_fma_f32 v[54:55], v[54:55], v[44:45], v[200:201]
	v_pk_fma_f32 v[204:205], v[98:99], v[52:53], v[204:205]
	v_add_f32_dpp v146, v92, v92 row_half_mirror row_mask:0xf bank_mask:0xa
	v_pk_fma_f32 v[204:205], v[100:101], v[54:55], v[204:205]
	ds_read_b128 v[178:181], v210 offset:10512
	ds_read_b128 v[84:87], v210 offset:10240
	v_add_f32_dpp v67, v67, v67 quad_perm:[1,0,3,2] row_mask:0xf bank_mask:0xf bound_ctrl:1
	v_add_f32_e32 v92, v204, v205
	ds_read_b128 v[184:187], v210 offset:11520
	ds_read_b32 v132, v211 offset:12032
	ds_read_b128 v[88:91], v210 offset:10256
	s_waitcnt lgkmcnt(5)
; template <int KG> __device__ __forceinline__ float redKG(float x) { x = red8d(x); if (KG == 16) x += dpp_rm(x); return x; }
; template <int MIX, int KPL, int KG>
; __device__ __forceinline__ float do_step(const StepIn<MIX, KPL>& s, float (&S)[KPL], const float gam) {
;     ...
;   } else {
;     float o0 = 0.f, o1 = 0.f;
; #pragma unroll
;     for (int i = 0; i < KPL; i += 2) {
;       const float d0 = (MIX == 3) ? gam : s.d[i], d1 = (MIX == 3) ? gam : s.d[i + 1];
;       S[i] = d0 * S[i] + s.k[i] * s.v; S[i + 1] = d1 * S[i + 1] + s.k[i + 1] * s.v;
;       o0 += s.q[i] * S[i]; o1 += s.q[i + 1] * S[i + 1];
;     }
;     return redKG<KG>(o0 + o1);
;   }
; template <int MIX>
; __device__ __forceinline__ void scan_part(const Params& p, const int layer, const int smp, const int b0, const int bstep, const int bend, const int h, const int part, char* lds, const int tid) {
;     ...
;     {
;       StepIn<MIX, KPL> sa, sb;
;       float osave = 0.f;
;       load_step<MIX, KPL>(qkdv, scal, 0, kg, col, sa);
;       for (int t = 0; t < ntok; t += 2) {
;         load_step<MIX, KPL>(qkdv, scal, t + 1, kg, col, sb);
;         __builtin_amdgcn_sched_barrier(0);
;         const float oa = do_step<MIX, KPL, KG>(sa, S, gam);
;         osave = (kg == (t & (KG - 1))) ? oa : osave;
;         load_step<MIX, KPL>(qkdv, scal, min(t + 2, ntok - 1), kg, col, sa);
;         __builtin_amdgcn_sched_barrier(0);
;         const float ob = do_step<MIX, KPL, KG>(sb, S, gam);
;         osave = (kg == ((t + 1) & (KG - 1))) ? ob : osave;
;         if (((t + 2) & (KG - 1)) == 0) obuf[(t + 2 - KG + kg) * CW + col] = osave;
;       }
;       const int remn = ntok & (KG - 1);
;       if (remn != 0 && kg < remn) obuf[(ntok - remn + kg) * CW + col] = osave;
;     }
	v_pk_mul_f32 v[134:135], v[138:139], v[102:103] op_sel_hi:[1,0]
	v_pk_mul_f32 v[158:159], v[140:141], v[102:103] op_sel_hi:[1,0]
	v_pk_fma_f32 v[30:31], v[30:31], v[44:45], v[134:135]
	ds_read_b128 v[188:191], v210 offset:11536
	ds_read_b128 v[94:97], v210 offset:11264
	v_add_f32_dpp v67, v67, v67 quad_perm:[2,3,0,1] row_mask:0xf bank_mask:0xf bound_ctrl:1
	v_add_f32_dpp v92, v92, v92 quad_perm:[1,0,3,2] row_mask:0xf bank_mask:0xf bound_ctrl:1
	v_pk_mul_f32 v[168:169], v[142:143], v[102:103] op_sel_hi:[1,0]
	v_pk_fma_f32 v[50:51], v[50:51], v[44:45], v[158:159]
	v_pk_mul_f32 v[202:203], v[68:69], v[30:31]
	v_pk_mul_f32 v[192:193], v[144:145], v[102:103] op_sel_hi:[1,0]
	v_pk_fma_f32 v[52:53], v[52:53], v[44:45], v[168:169]
	v_pk_fma_f32 v[202:203], v[70:71], v[50:51], v[202:203]
	ds_read_b128 v[98:101], v210 offset:11280
	v_pk_mul_f32 v[194:195], v[148:149], v[104:105] op_sel_hi:[1,0]
	v_pk_fma_f32 v[54:55], v[54:55], v[44:45], v[192:193]
	v_pk_fma_f32 v[202:203], v[72:73], v[52:53], v[202:203]
	v_pk_mul_f32 v[196:197], v[150:151], v[104:105] op_sel_hi:[1,0]
	v_pk_fma_f32 v[30:31], v[30:31], v[44:45], v[194:195]
	v_add_f32_dpp v182, v67, v67 row_half_mirror row_mask:0xf bank_mask:0x5
	v_add_f32_dpp v92, v92, v92 quad_perm:[2,3,0,1] row_mask:0xf bank_mask:0xf bound_ctrl:1
	v_pk_fma_f32 v[202:203], v[74:75], v[54:55], v[202:203]
	v_pk_mul_f32 v[198:199], v[152:153], v[104:105] op_sel_hi:[1,0]
	v_pk_fma_f32 v[50:51], v[50:51], v[44:45], v[196:197]
	v_pk_mul_f32 v[204:205], v[76:77], v[30:31]
	v_add_f32_e32 v67, v202, v203
	v_pk_mul_f32 v[200:201], v[154:155], v[104:105] op_sel_hi:[1,0]
	v_pk_fma_f32 v[52:53], v[52:53], v[44:45], v[198:199]
	v_pk_fma_f32 v[204:205], v[78:79], v[50:51], v[204:205]
	ds_read_b128 v[138:141], v210 offset:12544
	ds_read_b32 v102, v211 offset:13056
	v_pk_fma_f32 v[54:55], v[54:55], v[44:45], v[200:201]
	v_pk_fma_f32 v[204:205], v[80:81], v[52:53], v[204:205]
	v_add_f32_dpp v182, v92, v92 row_half_mirror row_mask:0xf bank_mask:0xa
	v_pk_fma_f32 v[204:205], v[82:83], v[54:55], v[204:205]
	ds_read_b128 v[142:145], v210 offset:12560
	ds_read_b128 v[68:71], v210 offset:12288
	v_add_f32_dpp v67, v67, v67 quad_perm:[1,0,3,2] row_mask:0xf bank_mask:0xf bound_ctrl:1
	v_add_f32_e32 v92, v204, v205
	ds_read_b128 v[148:151], v210 offset:13568
	ds_read_b32 v104, v211 offset:14080
	ds_read_b128 v[72:75], v210 offset:12304
	v_pk_mul_f32 v[134:135], v[174:175], v[106:107] op_sel_hi:[1,0]
	v_pk_mul_f32 v[158:159], v[176:177], v[106:107] op_sel_hi:[1,0]
	v_pk_fma_f32 v[30:31], v[30:31], v[44:45], v[134:135]
	ds_read_b128 v[152:155], v210 offset:13584
	ds_read_b128 v[76:79], v210 offset:13312
	v_add_f32_dpp v67, v67, v67 quad_perm:[2,3,0,1] row_mask:0xf bank_mask:0xf bound_ctrl:1
	v_add_f32_dpp v92, v92, v92 quad_perm:[1,0,3,2] row_mask:0xf bank_mask:0xf bound_ctrl:1
	s_waitcnt lgkmcnt(5)
	v_pk_mul_f32 v[168:169], v[178:179], v[106:107] op_sel_hi:[1,0]
	v_pk_fma_f32 v[50:51], v[50:51], v[44:45], v[158:159]
	v_pk_mul_f32 v[202:203], v[84:85], v[30:31]
	v_pk_mul_f32 v[192:193], v[180:181], v[106:107] op_sel_hi:[1,0]
	v_pk_fma_f32 v[52:53], v[52:53], v[44:45], v[168:169]
	v_pk_fma_f32 v[202:203], v[86:87], v[50:51], v[202:203]
	ds_read_b128 v[80:83], v210 offset:13328
	v_pk_mul_f32 v[194:195], v[184:185], v[132:133] op_sel_hi:[1,0]
	v_pk_fma_f32 v[54:55], v[54:55], v[44:45], v[192:193]
	v_pk_fma_f32 v[202:203], v[88:89], v[52:53], v[202:203]
	v_pk_mul_f32 v[196:197], v[186:187], v[132:133] op_sel_hi:[1,0]
	v_pk_fma_f32 v[30:31], v[30:31], v[44:45], v[194:195]
	v_add_f32_dpp v206, v67, v67 row_half_mirror row_mask:0xf bank_mask:0x5
	v_add_f32_dpp v92, v92, v92 quad_perm:[2,3,0,1] row_mask:0xf bank_mask:0xf bound_ctrl:1
	v_pk_fma_f32 v[202:203], v[90:91], v[54:55], v[202:203]
	v_pk_mul_f32 v[198:199], v[188:189], v[132:133] op_sel_hi:[1,0]
	v_pk_fma_f32 v[50:51], v[50:51], v[44:45], v[196:197]
	v_pk_mul_f32 v[204:205], v[94:95], v[30:31]
	v_add_f32_e32 v67, v202, v203
	v_pk_mul_f32 v[200:201], v[190:191], v[132:133] op_sel_hi:[1,0]
	v_pk_fma_f32 v[52:53], v[52:53], v[44:45], v[198:199]
	v_pk_fma_f32 v[204:205], v[96:97], v[50:51], v[204:205]
	ds_read_b128 v[174:177], v210 offset:14592
	ds_read_b32 v106, v211 offset:15104
	v_pk_fma_f32 v[54:55], v[54:55], v[44:45], v[200:201]
	v_pk_fma_f32 v[204:205], v[98:99], v[52:53], v[204:205]
	v_add_f32_dpp v206, v92, v92 row_half_mirror row_mask:0xf bank_mask:0xa
	v_pk_fma_f32 v[204:205], v[100:101], v[54:55], v[204:205]
	ds_read_b128 v[178:181], v210 offset:14608
	ds_read_b128 v[84:87], v210 offset:14336
	v_add_f32_dpp v67, v67, v67 quad_perm:[1,0,3,2] row_mask:0xf bank_mask:0xf bound_ctrl:1
	v_add_f32_e32 v92, v204, v205
	ds_read_b128 v[184:187], v210 offset:15616
	ds_read_b32 v132, v211 offset:16128
	ds_read_b128 v[88:91], v210 offset:14352
	v_pk_mul_f32 v[134:135], v[138:139], v[102:103] op_sel_hi:[1,0]
	v_pk_mul_f32 v[158:159], v[140:141], v[102:103] op_sel_hi:[1,0]
	v_pk_fma_f32 v[30:31], v[30:31], v[44:45], v[134:135]
	ds_read_b128 v[188:191], v210 offset:15632
	ds_read_b128 v[94:97], v210 offset:15360
	v_add_f32_dpp v67, v67, v67 quad_perm:[2,3,0,1] row_mask:0xf bank_mask:0xf bound_ctrl:1
	v_add_f32_dpp v92, v92, v92 quad_perm:[1,0,3,2] row_mask:0xf bank_mask:0xf bound_ctrl:1
	v_pk_mul_f32 v[168:169], v[142:143], v[102:103] op_sel_hi:[1,0]
	v_pk_fma_f32 v[50:51], v[50:51], v[44:45], v[158:159]
	v_pk_mul_f32 v[202:203], v[68:69], v[30:31]
	v_pk_mul_f32 v[192:193], v[144:145], v[102:103] op_sel_hi:[1,0]
	v_pk_fma_f32 v[52:53], v[52:53], v[44:45], v[168:169]
	v_pk_fma_f32 v[202:203], v[70:71], v[50:51], v[202:203]
	ds_read_b128 v[98:101], v210 offset:15376
	s_waitcnt lgkmcnt(3)
; template <int KG> __device__ __forceinline__ float redKG(float x) { x = red8d(x); if (KG == 16) x += dpp_rm(x); return x; }
; template <int MIX, int KPL, int KG>
; __device__ __forceinline__ float do_step(const StepIn<MIX, KPL>& s, float (&S)[KPL], const float gam) {
;     ...
;   } else {
;     float o0 = 0.f, o1 = 0.f;
; #pragma unroll
;     for (int i = 0; i < KPL; i += 2) {
;       const float d0 = (MIX == 3) ? gam : s.d[i], d1 = (MIX == 3) ? gam : s.d[i + 1];
;       S[i] = d0 * S[i] + s.k[i] * s.v; S[i + 1] = d1 * S[i + 1] + s.k[i + 1] * s.v;
;       o0 += s.q[i] * S[i]; o1 += s.q[i + 1] * S[i + 1];
;     }
;     return redKG<KG>(o0 + o1);
;   }
; template <int MIX>
; __device__ __forceinline__ void scan_part(const Params& p, const int layer, const int smp, const int b0, const int bstep, const int bend, const int h, const int part, char* lds, const int tid) {
;     ...
;     {
;       StepIn<MIX, KPL> sa, sb;
;       float osave = 0.f;
;       load_step<MIX, KPL>(qkdv, scal, 0, kg, col, sa);
;       for (int t = 0; t < ntok; t += 2) {
;         load_step<MIX, KPL>(qkdv, scal, t + 1, kg, col, sb);
;         __builtin_amdgcn_sched_barrier(0);
;         const float oa = do_step<MIX, KPL, KG>(sa, S, gam);
;         osave = (kg == (t & (KG - 1))) ? oa : osave;
;         load_step<MIX, KPL>(qkdv, scal, min(t + 2, ntok - 1), kg, col, sa);
;         __builtin_amdgcn_sched_barrier(0);
;         const float ob = do_step<MIX, KPL, KG>(sb, S, gam);
;         osave = (kg == ((t + 1) & (KG - 1))) ? ob : osave;
;         if (((t + 2) & (KG - 1)) == 0) obuf[(t + 2 - KG + kg) * CW + col] = osave;
;       }
;       const int remn = ntok & (KG - 1);
;       if (remn != 0 && kg < remn) obuf[(ntok - remn + kg) * CW + col] = osave;
;     }
	v_pk_mul_f32 v[194:195], v[148:149], v[104:105] op_sel_hi:[1,0]
	v_pk_fma_f32 v[54:55], v[54:55], v[44:45], v[192:193]
	v_pk_fma_f32 v[202:203], v[72:73], v[52:53], v[202:203]
	v_pk_mul_f32 v[196:197], v[150:151], v[104:105] op_sel_hi:[1,0]
	v_pk_fma_f32 v[30:31], v[30:31], v[44:45], v[194:195]
	v_add_f32_dpp v207, v67, v67 row_half_mirror row_mask:0xf bank_mask:0x5
	v_add_f32_dpp v92, v92, v92 quad_perm:[2,3,0,1] row_mask:0xf bank_mask:0xf bound_ctrl:1
	v_pk_fma_f32 v[202:203], v[74:75], v[54:55], v[202:203]
	v_pk_mul_f32 v[198:199], v[152:153], v[104:105] op_sel_hi:[1,0]
	v_pk_fma_f32 v[50:51], v[50:51], v[44:45], v[196:197]
	v_pk_mul_f32 v[204:205], v[76:77], v[30:31]
	v_add_f32_e32 v67, v202, v203
	v_pk_mul_f32 v[200:201], v[154:155], v[104:105] op_sel_hi:[1,0]
	v_pk_fma_f32 v[52:53], v[52:53], v[44:45], v[198:199]
	v_pk_fma_f32 v[204:205], v[78:79], v[50:51], v[204:205]
	v_pk_fma_f32 v[54:55], v[54:55], v[44:45], v[200:201]
	v_pk_fma_f32 v[204:205], v[80:81], v[52:53], v[204:205]
	v_add_f32_dpp v207, v92, v92 row_half_mirror row_mask:0xf bank_mask:0xa
	v_pk_fma_f32 v[204:205], v[82:83], v[54:55], v[204:205]
	v_add_f32_dpp v67, v67, v67 quad_perm:[1,0,3,2] row_mask:0xf bank_mask:0xf bound_ctrl:1
	v_add_f32_e32 v92, v204, v205
	v_pk_mul_f32 v[134:135], v[174:175], v[106:107] op_sel_hi:[1,0]
	v_pk_mul_f32 v[158:159], v[176:177], v[106:107] op_sel_hi:[1,0]
	v_pk_fma_f32 v[30:31], v[30:31], v[44:45], v[134:135]
	v_add_f32_dpp v67, v67, v67 quad_perm:[2,3,0,1] row_mask:0xf bank_mask:0xf bound_ctrl:1
	v_add_f32_dpp v92, v92, v92 quad_perm:[1,0,3,2] row_mask:0xf bank_mask:0xf bound_ctrl:1
	v_pk_mul_f32 v[168:169], v[178:179], v[106:107] op_sel_hi:[1,0]
	v_pk_fma_f32 v[50:51], v[50:51], v[44:45], v[158:159]
	v_pk_mul_f32 v[202:203], v[84:85], v[30:31]
	v_pk_mul_f32 v[192:193], v[180:181], v[106:107] op_sel_hi:[1,0]
	v_pk_fma_f32 v[52:53], v[52:53], v[44:45], v[168:169]
	v_pk_fma_f32 v[202:203], v[86:87], v[50:51], v[202:203]
	v_pk_mul_f32 v[194:195], v[184:185], v[132:133] op_sel_hi:[1,0]
	v_pk_fma_f32 v[54:55], v[54:55], v[44:45], v[192:193]
	v_pk_fma_f32 v[202:203], v[88:89], v[52:53], v[202:203]
	v_pk_mul_f32 v[196:197], v[186:187], v[132:133] op_sel_hi:[1,0]
	v_pk_fma_f32 v[30:31], v[30:31], v[44:45], v[194:195]
	v_add_f32_dpp v208, v67, v67 row_half_mirror row_mask:0xf bank_mask:0x5
	v_add_f32_dpp v92, v92, v92 quad_perm:[2,3,0,1] row_mask:0xf bank_mask:0xf bound_ctrl:1
	v_pk_fma_f32 v[202:203], v[90:91], v[54:55], v[202:203]
	s_waitcnt lgkmcnt(0)
	v_pk_mul_f32 v[198:199], v[188:189], v[132:133] op_sel_hi:[1,0]
	v_pk_fma_f32 v[50:51], v[50:51], v[44:45], v[196:197]
	v_pk_mul_f32 v[204:205], v[94:95], v[30:31]
	v_add_f32_e32 v67, v202, v203
	v_pk_mul_f32 v[200:201], v[190:191], v[132:133] op_sel_hi:[1,0]
	v_pk_fma_f32 v[52:53], v[52:53], v[44:45], v[198:199]
	v_pk_fma_f32 v[204:205], v[96:97], v[50:51], v[204:205]
	v_pk_fma_f32 v[54:55], v[54:55], v[44:45], v[200:201]
	v_pk_fma_f32 v[204:205], v[98:99], v[52:53], v[204:205]
	v_add_f32_dpp v208, v92, v92 row_half_mirror row_mask:0xf bank_mask:0xa
	v_pk_fma_f32 v[204:205], v[100:101], v[54:55], v[204:205]
	v_add_f32_dpp v67, v67, v67 quad_perm:[1,0,3,2] row_mask:0xf bank_mask:0xf bound_ctrl:1
	v_add_f32_e32 v92, v204, v205
	ds_read_b128 v[138:141], v210 offset:16640
	v_add_f32_dpp v67, v67, v67 quad_perm:[2,3,0,1] row_mask:0xf bank_mask:0xf bound_ctrl:1
	v_add_f32_dpp v92, v92, v92 quad_perm:[1,0,3,2] row_mask:0xf bank_mask:0xf bound_ctrl:1
	ds_read_b128 v[142:145], v210 offset:16656
	v_add_f32_dpp v209, v67, v67 row_half_mirror row_mask:0xf bank_mask:0x5
	v_add_f32_dpp v92, v92, v92 quad_perm:[2,3,0,1] row_mask:0xf bank_mask:0xf bound_ctrl:1
	ds_read_b32 v102, v211 offset:17152
	ds_read_b128 v[68:71], v210 offset:16384
	v_add_f32_dpp v209, v92, v92 row_half_mirror row_mask:0xf bank_mask:0xa
	ds_read_b128 v[72:75], v210 offset:16400
	ds_read_b128 v[148:151], v210 offset:17664
	ds_read_b128 v[152:155], v210 offset:17680
	ds_read_b32 v104, v211 offset:18176
	ds_read_b128 v[76:79], v210 offset:17408
	ds_read_b128 v[80:83], v210 offset:17424
	ds_write_b32 v212, v131 offset:32768
	ds_write_b32 v212, v136 offset:33024
	ds_write_b32 v212, v146 offset:33280
	ds_write_b32 v212, v182 offset:33536
	ds_write_b32 v212, v206 offset:33792
	ds_write_b32 v212, v207 offset:34048
	ds_write_b32 v212, v208 offset:34304
	ds_write_b32 v212, v209 offset:34560
	v_add_u32_e32 v210, 0x4000, v210
	v_add_u32_e32 v211, 0x4000, v211
	v_add_u32_e32 v212, 0x800, v212
	s_sub_i32 s43, s43, 1
	s_cmp_lg_u32 s43, 0
	s_cbranch_scc1 .Lscan3p_blk

; template <int KG> __device__ __forceinline__ float redKG(float x) { x = red8d(x); if (KG == 16) x += dpp_rm(x); return x; }
; template <int MIX, int KPL, int KG>
; __device__ __forceinline__ float do_step(const StepIn<MIX, KPL>& s, float (&S)[KPL], const float gam) {
;     ...
;   } else {
;     float o0 = 0.f, o1 = 0.f;
; #pragma unroll
;     for (int i = 0; i < KPL; i += 2) {
;       const float d0 = (MIX == 3) ? gam : s.d[i], d1 = (MIX == 3) ? gam : s.d[i + 1];
;       S[i] = d0 * S[i] + s.k[i] * s.v; S[i + 1] = d1 * S[i + 1] + s.k[i + 1] * s.v;
;       o0 += s.q[i] * S[i]; o1 += s.q[i + 1] * S[i + 1];
;     }
;     return redKG<KG>(o0 + o1);
;   }
; template <int MIX>
; __device__ __forceinline__ void scan_part(const Params& p, const int layer, const int smp, const int b0, const int bstep, const int bend, const int h, const int part, char* lds, const int tid) {
;     ...
;     {
;       StepIn<MIX, KPL> sa, sb;
;       float osave = 0.f;
;       load_step<MIX, KPL>(qkdv, scal, 0, kg, col, sa);
;       for (int t = 0; t < ntok; t += 2) {
;         load_step<MIX, KPL>(qkdv, scal, t + 1, kg, col, sb);
;         __builtin_amdgcn_sched_barrier(0);
;         const float oa = do_step<MIX, KPL, KG>(sa, S, gam);
;         osave = (kg == (t & (KG - 1))) ? oa : osave;
;         load_step<MIX, KPL>(qkdv, scal, min(t + 2, ntok - 1), kg, col, sa);
;         __builtin_amdgcn_sched_barrier(0);
;         const float ob = do_step<MIX, KPL, KG>(sb, S, gam);
;         osave = (kg == ((t + 1) & (KG - 1))) ? ob : osave;
;         if (((t + 2) & (KG - 1)) == 0) obuf[(t + 2 - KG + kg) * CW + col] = osave;
;       }
;       const int remn = ntok & (KG - 1);
;       if (remn != 0 && kg < remn) obuf[(ntok - remn + kg) * CW + col] = osave;
;     }
.LBB0_358:
	v_mov_b32_e32 v178, v47
	v_mov_b32_e32 v179, v48
	v_and_b32_e32 v180, 4, v43
	s_lshr_b32 s43, s29, 4
	v_lshl_add_u32 v180, v180, 5, v48
	ds_read_b128 v[74:77], v178 offset:256
	ds_read_b32 v78, v179 offset:768
	ds_read_b128 v[98:101], v178 offset:512
	ds_read_b128 v[58:61], v178
	ds_read_b128 v[84:87], v178 offset:1280
	ds_read_b32 v106, v179 offset:1792
	ds_read_b128 v[102:105], v178 offset:1536
	ds_read_b128 v[62:65], v178 offset:1024
.Lscan2p_blk:
	s_waitcnt lgkmcnt(4)
	ds_read_b128 v[88:91], v178 offset:2304
	ds_read_b32 v142, v179 offset:2816
	ds_read_b128 v[132:135], v178 offset:2560
	ds_read_b128 v[66:69], v178 offset:2048
	ds_read_b128 v[94:97], v178 offset:3328
	ds_read_b32 v144, v179 offset:3840
	v_pk_mul_f32 v[148:149], v[74:75], v[78:79] op_sel_hi:[1,0]
	ds_read_b128 v[138:141], v178 offset:3584
	v_pk_mul_f32 v[150:151], v[76:77], v[78:79] op_sel_hi:[1,0]
	v_pk_fma_f32 v[28:29], v[28:29], v[98:99], v[148:149]
	ds_read_b128 v[70:73], v178 offset:3072
	v_pk_fma_f32 v[40:41], v[40:41], v[100:101], v[150:151]
	v_pk_mul_f32 v[158:159], v[58:59], v[28:29]
	v_pk_fma_f32 v[158:159], v[60:61], v[40:41], v[158:159]
	s_waitcnt lgkmcnt(5)
	v_pk_mul_f32 v[152:153], v[84:85], v[106:107] op_sel_hi:[1,0]
	v_add_f32_e32 v80, v158, v159
	v_pk_mul_f32 v[154:155], v[86:87], v[106:107] op_sel_hi:[1,0]
	v_pk_fma_f32 v[28:29], v[28:29], v[102:103], v[152:153]
	v_pk_fma_f32 v[40:41], v[40:41], v[104:105], v[154:155]
	v_pk_mul_f32 v[168:169], v[62:63], v[28:29]
	v_pk_fma_f32 v[168:169], v[64:65], v[40:41], v[168:169]
	ds_read_b128 v[74:77], v178 offset:4352
	ds_read_b32 v78, v179 offset:4864
	v_add_f32_dpp v80, v80, v80 quad_perm:[1,0,3,2] row_mask:0xf bank_mask:0xf bound_ctrl:1
	v_add_f32_e32 v82, v168, v169
	ds_read_b128 v[98:101], v178 offset:4608
	ds_read_b128 v[58:61], v178 offset:4096
	ds_read_b128 v[84:87], v178 offset:5376
	ds_read_b32 v106, v179 offset:5888
	v_add_f32_dpp v80, v80, v80 quad_perm:[2,3,0,1] row_mask:0xf bank_mask:0xf bound_ctrl:1
	v_add_f32_dpp v82, v82, v82 quad_perm:[1,0,3,2] row_mask:0xf bank_mask:0xf bound_ctrl:1
	v_pk_mul_f32 v[148:149], v[88:89], v[142:143] op_sel_hi:[1,0]
	ds_read_b128 v[102:105], v178 offset:5632
	v_pk_mul_f32 v[150:151], v[90:91], v[142:143] op_sel_hi:[1,0]
	v_pk_fma_f32 v[28:29], v[28:29], v[132:133], v[148:149]
	ds_read_b128 v[62:65], v178 offset:5120
	v_pk_fma_f32 v[40:41], v[40:41], v[134:135], v[150:151]
	s_waitcnt lgkmcnt(5)
	v_pk_mul_f32 v[158:159], v[66:67], v[28:29]
	v_add_f32_dpp v92, v80, v80 row_half_mirror row_mask:0xf bank_mask:0x5
	v_add_f32_dpp v82, v82, v82 quad_perm:[2,3,0,1] row_mask:0xf bank_mask:0xf bound_ctrl:1
	v_pk_fma_f32 v[158:159], v[68:69], v[40:41], v[158:159]
	v_pk_mul_f32 v[152:153], v[94:95], v[144:145] op_sel_hi:[1,0]
	v_add_f32_e32 v80, v158, v159
	v_pk_mul_f32 v[154:155], v[96:97], v[144:145] op_sel_hi:[1,0]
	v_pk_fma_f32 v[28:29], v[28:29], v[138:139], v[152:153]
	v_pk_fma_f32 v[40:41], v[40:41], v[140:141], v[154:155]
	v_pk_mul_f32 v[168:169], v[70:71], v[28:29]
	v_add_f32_dpp v92, v82, v82 row_half_mirror row_mask:0xf bank_mask:0xa
	v_pk_fma_f32 v[168:169], v[72:73], v[40:41], v[168:169]
	ds_read_b128 v[88:91], v178 offset:6400
	ds_read_b32 v142, v179 offset:6912
	v_add_f32_dpp v80, v80, v80 quad_perm:[1,0,3,2] row_mask:0xf bank_mask:0xf bound_ctrl:1
	v_add_f32_e32 v82, v168, v169
	ds_read_b128 v[132:135], v178 offset:6656
	ds_read_b128 v[66:69], v178 offset:6144
	ds_read_b128 v[94:97], v178 offset:7424
	ds_read_b32 v144, v179 offset:7936
	v_add_f32_dpp v80, v80, v80 quad_perm:[2,3,0,1] row_mask:0xf bank_mask:0xf bound_ctrl:1
	v_add_f32_dpp v82, v82, v82 quad_perm:[1,0,3,2] row_mask:0xf bank_mask:0xf bound_ctrl:1
	v_pk_mul_f32 v[148:149], v[74:75], v[78:79] op_sel_hi:[1,0]
	ds_read_b128 v[138:141], v178 offset:7680
	v_pk_mul_f32 v[150:151], v[76:77], v[78:79] op_sel_hi:[1,0]
	v_pk_fma_f32 v[28:29], v[28:29], v[98:99], v[148:149]
	ds_read_b128 v[70:73], v178 offset:7168
	v_pk_fma_f32 v[40:41], v[40:41], v[100:101], v[150:151]
	s_waitcnt lgkmcnt(5)
	v_pk_mul_f32 v[158:159], v[58:59], v[28:29]
	v_add_f32_dpp v131, v80, v80 row_half_mirror row_mask:0xf bank_mask:0x5
	v_add_f32_dpp v82, v82, v82 quad_perm:[2,3,0,1] row_mask:0xf bank_mask:0xf bound_ctrl:1
	v_pk_fma_f32 v[158:159], v[60:61], v[40:41], v[158:159]
	v_pk_mul_f32 v[152:153], v[84:85], v[106:107] op_sel_hi:[1,0]
	v_add_f32_e32 v80, v158, v159
	v_pk_mul_f32 v[154:155], v[86:87], v[106:107] op_sel_hi:[1,0]
	v_pk_fma_f32 v[28:29], v[28:29], v[102:103], v[152:153]
	v_pk_fma_f32 v[40:41], v[40:41], v[104:105], v[154:155]
	v_pk_mul_f32 v[168:169], v[62:63], v[28:29]
	v_add_f32_dpp v131, v82, v82 row_half_mirror row_mask:0xf bank_mask:0xa
	v_pk_fma_f32 v[168:169], v[64:65], v[40:41], v[168:169]
	ds_read_b128 v[74:77], v178 offset:8448
	ds_read_b32 v78, v179 offset:8960
	v_add_f32_dpp v80, v80, v80 quad_perm:[1,0,3,2] row_mask:0xf bank_mask:0xf bound_ctrl:1
	v_add_f32_e32 v82, v168, v169
	ds_read_b128 v[98:101], v178 offset:8704
	ds_read_b128 v[58:61], v178 offset:8192
	ds_read_b128 v[84:87], v178 offset:9472
	ds_read_b32 v106, v179 offset:9984
	v_add_f32_dpp v80, v80, v80 quad_perm:[2,3,0,1] row_mask:0xf bank_mask:0xf bound_ctrl:1
	v_add_f32_dpp v82, v82, v82 quad_perm:[1,0,3,2] row_mask:0xf bank_mask:0xf bound_ctrl:1
	v_pk_mul_f32 v[148:149], v[88:89], v[142:143] op_sel_hi:[1,0]
	ds_read_b128 v[102:105], v178 offset:9728
	v_pk_mul_f32 v[150:151], v[90:91], v[142:143] op_sel_hi:[1,0]
	v_pk_fma_f32 v[28:29], v[28:29], v[132:133], v[148:149]
	ds_read_b128 v[62:65], v178 offset:9216
	v_pk_fma_f32 v[40:41], v[40:41], v[134:135], v[150:151]
	s_waitcnt lgkmcnt(5)
; template <int KG> __device__ __forceinline__ float redKG(float x) { x = red8d(x); if (KG == 16) x += dpp_rm(x); return x; }
; template <int MIX, int KPL, int KG>
; __device__ __forceinline__ float do_step(const StepIn<MIX, KPL>& s, float (&S)[KPL], const float gam) {
;     ...
;   } else {
;     float o0 = 0.f, o1 = 0.f;
; #pragma unroll
;     for (int i = 0; i < KPL; i += 2) {
;       const float d0 = (MIX == 3) ? gam : s.d[i], d1 = (MIX == 3) ? gam : s.d[i + 1];
;       S[i] = d0 * S[i] + s.k[i] * s.v; S[i + 1] = d1 * S[i + 1] + s.k[i + 1] * s.v;
;       o0 += s.q[i] * S[i]; o1 += s.q[i + 1] * S[i + 1];
;     }
;     return redKG<KG>(o0 + o1);
;   }
; template <int MIX>
; __device__ __forceinline__ void scan_part(const Params& p, const int layer, const int smp, const int b0, const int bstep, const int bend, const int h, const int part, char* lds, const int tid) {
;     ...
;     {
;       StepIn<MIX, KPL> sa, sb;
;       float osave = 0.f;
;       load_step<MIX, KPL>(qkdv, scal, 0, kg, col, sa);
;       for (int t = 0; t < ntok; t += 2) {
;         load_step<MIX, KPL>(qkdv, scal, t + 1, kg, col, sb);
;         __builtin_amdgcn_sched_barrier(0);
;         const float oa = do_step<MIX, KPL, KG>(sa, S, gam);
;         osave = (kg == (t & (KG - 1))) ? oa : osave;
;         load_step<MIX, KPL>(qkdv, scal, min(t + 2, ntok - 1), kg, col, sa);
;         __builtin_amdgcn_sched_barrier(0);
;         const float ob = do_step<MIX, KPL, KG>(sb, S, gam);
;         osave = (kg == ((t + 1) & (KG - 1))) ? ob : osave;
;         if (((t + 2) & (KG - 1)) == 0) obuf[(t + 2 - KG + kg) * CW + col] = osave;
;       }
;       const int remn = ntok & (KG - 1);
;       if (remn != 0 && kg < remn) obuf[(ntok - remn + kg) * CW + col] = osave;
;     }
	v_pk_mul_f32 v[158:159], v[66:67], v[28:29]
	v_add_f32_dpp v136, v80, v80 row_half_mirror row_mask:0xf bank_mask:0x5
	v_add_f32_dpp v82, v82, v82 quad_perm:[2,3,0,1] row_mask:0xf bank_mask:0xf bound_ctrl:1
	v_pk_fma_f32 v[158:159], v[68:69], v[40:41], v[158:159]
	v_pk_mul_f32 v[152:153], v[94:95], v[144:145] op_sel_hi:[1,0]
	v_add_f32_e32 v80, v158, v159
	v_pk_mul_f32 v[154:155], v[96:97], v[144:145] op_sel_hi:[1,0]
	v_pk_fma_f32 v[28:29], v[28:29], v[138:139], v[152:153]
	v_pk_fma_f32 v[40:41], v[40:41], v[140:141], v[154:155]
	v_pk_mul_f32 v[168:169], v[70:71], v[28:29]
	v_add_f32_dpp v136, v82, v82 row_half_mirror row_mask:0xf bank_mask:0xa
	v_pk_fma_f32 v[168:169], v[72:73], v[40:41], v[168:169]
	ds_read_b128 v[88:91], v178 offset:10496
	ds_read_b32 v142, v179 offset:11008
	v_add_f32_dpp v80, v80, v80 quad_perm:[1,0,3,2] row_mask:0xf bank_mask:0xf bound_ctrl:1
	v_add_f32_e32 v82, v168, v169
	ds_read_b128 v[132:135], v178 offset:10752
	ds_read_b128 v[66:69], v178 offset:10240
	ds_read_b128 v[94:97], v178 offset:11520
	ds_read_b32 v144, v179 offset:12032
	v_add_f32_dpp v80, v80, v80 quad_perm:[2,3,0,1] row_mask:0xf bank_mask:0xf bound_ctrl:1
	v_add_f32_dpp v82, v82, v82 quad_perm:[1,0,3,2] row_mask:0xf bank_mask:0xf bound_ctrl:1
	v_pk_mul_f32 v[148:149], v[74:75], v[78:79] op_sel_hi:[1,0]
	ds_read_b128 v[138:141], v178 offset:11776
	v_pk_mul_f32 v[150:151], v[76:77], v[78:79] op_sel_hi:[1,0]
	v_pk_fma_f32 v[28:29], v[28:29], v[98:99], v[148:149]
	ds_read_b128 v[70:73], v178 offset:11264
	v_pk_fma_f32 v[40:41], v[40:41], v[100:101], v[150:151]
	s_waitcnt lgkmcnt(5)
	v_pk_mul_f32 v[158:159], v[58:59], v[28:29]
	v_add_f32_dpp v146, v80, v80 row_half_mirror row_mask:0xf bank_mask:0x5
	v_add_f32_dpp v82, v82, v82 quad_perm:[2,3,0,1] row_mask:0xf bank_mask:0xf bound_ctrl:1
	v_pk_fma_f32 v[158:159], v[60:61], v[40:41], v[158:159]
	v_pk_mul_f32 v[152:153], v[84:85], v[106:107] op_sel_hi:[1,0]
	v_add_f32_e32 v80, v158, v159
	v_pk_mul_f32 v[154:155], v[86:87], v[106:107] op_sel_hi:[1,0]
	v_pk_fma_f32 v[28:29], v[28:29], v[102:103], v[152:153]
	v_pk_fma_f32 v[40:41], v[40:41], v[104:105], v[154:155]
	v_pk_mul_f32 v[168:169], v[62:63], v[28:29]
	v_add_f32_dpp v146, v82, v82 row_half_mirror row_mask:0xf bank_mask:0xa
	v_pk_fma_f32 v[168:169], v[64:65], v[40:41], v[168:169]
	ds_read_b128 v[74:77], v178 offset:12544
	ds_read_b32 v78, v179 offset:13056
	v_add_f32_dpp v80, v80, v80 quad_perm:[1,0,3,2] row_mask:0xf bank_mask:0xf bound_ctrl:1
	v_add_f32_e32 v82, v168, v169
	ds_read_b128 v[98:101], v178 offset:12800
	ds_read_b128 v[58:61], v178 offset:12288
	ds_read_b128 v[84:87], v178 offset:13568
	ds_read_b32 v106, v179 offset:14080
	v_add_f32_dpp v80, v80, v80 quad_perm:[2,3,0,1] row_mask:0xf bank_mask:0xf bound_ctrl:1
	v_add_f32_dpp v82, v82, v82 quad_perm:[1,0,3,2] row_mask:0xf bank_mask:0xf bound_ctrl:1
	v_pk_mul_f32 v[148:149], v[88:89], v[142:143] op_sel_hi:[1,0]
	ds_read_b128 v[102:105], v178 offset:13824
	v_pk_mul_f32 v[150:151], v[90:91], v[142:143] op_sel_hi:[1,0]
	v_pk_fma_f32 v[28:29], v[28:29], v[132:133], v[148:149]
	ds_read_b128 v[62:65], v178 offset:13312
	v_pk_fma_f32 v[40:41], v[40:41], v[134:135], v[150:151]
	s_waitcnt lgkmcnt(5)
	v_pk_mul_f32 v[158:159], v[66:67], v[28:29]
	v_add_f32_dpp v174, v80, v80 row_half_mirror row_mask:0xf bank_mask:0x5
	v_add_f32_dpp v82, v82, v82 quad_perm:[2,3,0,1] row_mask:0xf bank_mask:0xf bound_ctrl:1
	v_pk_fma_f32 v[158:159], v[68:69], v[40:41], v[158:159]
	v_pk_mul_f32 v[152:153], v[94:95], v[144:145] op_sel_hi:[1,0]
	v_add_f32_e32 v80, v158, v159
	v_pk_mul_f32 v[154:155], v[96:97], v[144:145] op_sel_hi:[1,0]
	v_pk_fma_f32 v[28:29], v[28:29], v[138:139], v[152:153]
	v_pk_fma_f32 v[40:41], v[40:41], v[140:141], v[154:155]
	v_pk_mul_f32 v[168:169], v[70:71], v[28:29]
	v_add_f32_dpp v174, v82, v82 row_half_mirror row_mask:0xf bank_mask:0xa
	v_pk_fma_f32 v[168:169], v[72:73], v[40:41], v[168:169]
	ds_read_b128 v[88:91], v178 offset:14592
	ds_read_b32 v142, v179 offset:15104
	v_add_f32_dpp v80, v80, v80 quad_perm:[1,0,3,2] row_mask:0xf bank_mask:0xf bound_ctrl:1
	v_add_f32_e32 v82, v168, v169
	ds_read_b128 v[132:135], v178 offset:14848
	ds_read_b128 v[66:69], v178 offset:14336
	ds_read_b128 v[94:97], v178 offset:15616
	ds_read_b32 v144, v179 offset:16128
	v_add_f32_dpp v80, v80, v80 quad_perm:[2,3,0,1] row_mask:0xf bank_mask:0xf bound_ctrl:1
	v_add_f32_dpp v82, v82, v82 quad_perm:[1,0,3,2] row_mask:0xf bank_mask:0xf bound_ctrl:1
	v_pk_mul_f32 v[148:149], v[74:75], v[78:79] op_sel_hi:[1,0]
	ds_read_b128 v[138:141], v178 offset:15872
	v_pk_mul_f32 v[150:151], v[76:77], v[78:79] op_sel_hi:[1,0]
	v_pk_fma_f32 v[28:29], v[28:29], v[98:99], v[148:149]
	ds_read_b128 v[70:73], v178 offset:15360
	v_pk_fma_f32 v[40:41], v[40:41], v[100:101], v[150:151]
	s_waitcnt lgkmcnt(5)
; template <int KG> __device__ __forceinline__ float redKG(float x) { x = red8d(x); if (KG == 16) x += dpp_rm(x); return x; }
; template <int MIX, int KPL, int KG>
; __device__ __forceinline__ float do_step(const StepIn<MIX, KPL>& s, float (&S)[KPL], const float gam) {
;     ...
;   } else {
;     float o0 = 0.f, o1 = 0.f;
; #pragma unroll
;     for (int i = 0; i < KPL; i += 2) {
;       const float d0 = (MIX == 3) ? gam : s.d[i], d1 = (MIX == 3) ? gam : s.d[i + 1];
;       S[i] = d0 * S[i] + s.k[i] * s.v; S[i + 1] = d1 * S[i + 1] + s.k[i + 1] * s.v;
;       o0 += s.q[i] * S[i]; o1 += s.q[i + 1] * S[i + 1];
;     }
;     return redKG<KG>(o0 + o1);
;   }
; template <int MIX>
; __device__ __forceinline__ void scan_part(const Params& p, const int layer, const int smp, const int b0, const int bstep, const int bend, const int h, const int part, char* lds, const int tid) {
;     ...
;     {
;       StepIn<MIX, KPL> sa, sb;
;       float osave = 0.f;
;       load_step<MIX, KPL>(qkdv, scal, 0, kg, col, sa);
;       for (int t = 0; t < ntok; t += 2) {
;         load_step<MIX, KPL>(qkdv, scal, t + 1, kg, col, sb);
;         __builtin_amdgcn_sched_barrier(0);
;         const float oa = do_step<MIX, KPL, KG>(sa, S, gam);
;         osave = (kg == (t & (KG - 1))) ? oa : osave;
;         load_step<MIX, KPL>(qkdv, scal, min(t + 2, ntok - 1), kg, col, sa);
;         __builtin_amdgcn_sched_barrier(0);
;         const float ob = do_step<MIX, KPL, KG>(sb, S, gam);
;         osave = (kg == ((t + 1) & (KG - 1))) ? ob : osave;
;         if (((t + 2) & (KG - 1)) == 0) obuf[(t + 2 - KG + kg) * CW + col] = osave;
;       }
;       const int remn = ntok & (KG - 1);
;       if (remn != 0 && kg < remn) obuf[(ntok - remn + kg) * CW + col] = osave;
;     }
	v_pk_mul_f32 v[158:159], v[58:59], v[28:29]
	v_add_f32_dpp v175, v80, v80 row_half_mirror row_mask:0xf bank_mask:0x5
	v_add_f32_dpp v82, v82, v82 quad_perm:[2,3,0,1] row_mask:0xf bank_mask:0xf bound_ctrl:1
	v_pk_fma_f32 v[158:159], v[60:61], v[40:41], v[158:159]
	v_pk_mul_f32 v[152:153], v[84:85], v[106:107] op_sel_hi:[1,0]
	v_add_f32_e32 v80, v158, v159
	v_pk_mul_f32 v[154:155], v[86:87], v[106:107] op_sel_hi:[1,0]
	v_pk_fma_f32 v[28:29], v[28:29], v[102:103], v[152:153]
	v_pk_fma_f32 v[40:41], v[40:41], v[104:105], v[154:155]
	v_pk_mul_f32 v[168:169], v[62:63], v[28:29]
	v_add_f32_dpp v175, v82, v82 row_half_mirror row_mask:0xf bank_mask:0xa
	v_pk_fma_f32 v[168:169], v[64:65], v[40:41], v[168:169]
	v_add_f32_dpp v80, v80, v80 quad_perm:[1,0,3,2] row_mask:0xf bank_mask:0xf bound_ctrl:1
	v_add_f32_e32 v82, v168, v169
	v_pk_mul_f32 v[148:149], v[88:89], v[142:143] op_sel_hi:[1,0]
	v_add_f32_dpp v80, v80, v80 quad_perm:[2,3,0,1] row_mask:0xf bank_mask:0xf bound_ctrl:1
	v_add_f32_dpp v82, v82, v82 quad_perm:[1,0,3,2] row_mask:0xf bank_mask:0xf bound_ctrl:1
	v_pk_mul_f32 v[150:151], v[90:91], v[142:143] op_sel_hi:[1,0]
	v_pk_fma_f32 v[28:29], v[28:29], v[132:133], v[148:149]
	v_pk_fma_f32 v[40:41], v[40:41], v[134:135], v[150:151]
	s_waitcnt lgkmcnt(0)
	v_pk_mul_f32 v[158:159], v[66:67], v[28:29]
	v_add_f32_dpp v176, v80, v80 row_half_mirror row_mask:0xf bank_mask:0x5
	v_add_f32_dpp v82, v82, v82 quad_perm:[2,3,0,1] row_mask:0xf bank_mask:0xf bound_ctrl:1
	v_pk_fma_f32 v[158:159], v[68:69], v[40:41], v[158:159]
	v_pk_mul_f32 v[152:153], v[94:95], v[144:145] op_sel_hi:[1,0]
	v_add_f32_e32 v80, v158, v159
	v_pk_mul_f32 v[154:155], v[96:97], v[144:145] op_sel_hi:[1,0]
	v_pk_fma_f32 v[28:29], v[28:29], v[138:139], v[152:153]
	v_pk_fma_f32 v[40:41], v[40:41], v[140:141], v[154:155]
	v_pk_mul_f32 v[168:169], v[70:71], v[28:29]
	v_add_f32_dpp v176, v82, v82 row_half_mirror row_mask:0xf bank_mask:0xa
	v_pk_fma_f32 v[168:169], v[72:73], v[40:41], v[168:169]
	v_add_f32_dpp v80, v80, v80 quad_perm:[1,0,3,2] row_mask:0xf bank_mask:0xf bound_ctrl:1
	v_add_f32_e32 v82, v168, v169
	ds_read_b128 v[74:77], v178 offset:16640
	v_add_f32_dpp v80, v80, v80 quad_perm:[2,3,0,1] row_mask:0xf bank_mask:0xf bound_ctrl:1
	v_add_f32_dpp v82, v82, v82 quad_perm:[1,0,3,2] row_mask:0xf bank_mask:0xf bound_ctrl:1
	ds_read_b32 v78, v179 offset:17152
	v_add_f32_dpp v177, v80, v80 row_half_mirror row_mask:0xf bank_mask:0x5
	v_add_f32_dpp v82, v82, v82 quad_perm:[2,3,0,1] row_mask:0xf bank_mask:0xf bound_ctrl:1
	ds_read_b128 v[98:101], v178 offset:16896
	ds_read_b128 v[58:61], v178 offset:16384
	v_add_f32_dpp v177, v82, v82 row_half_mirror row_mask:0xf bank_mask:0xa
	ds_read_b128 v[84:87], v178 offset:17664
	ds_read_b32 v106, v179 offset:18176
	ds_read_b128 v[102:105], v178 offset:17920
	ds_read_b128 v[62:65], v178 offset:17408
	ds_write_b32 v180, v92 offset:32768
	ds_write_b32 v180, v131 offset:33024
	ds_write_b32 v180, v136 offset:33280
	ds_write_b32 v180, v146 offset:33536
	ds_write_b32 v180, v174 offset:33792
	ds_write_b32 v180, v175 offset:34048
	ds_write_b32 v180, v176 offset:34304
	ds_write_b32 v180, v177 offset:34560
	v_add_u32_e32 v178, 0x4000, v178
	v_add_u32_e32 v179, 0x4000, v179
	v_add_u32_e32 v180, 0x800, v180
	s_sub_i32 s43, s43, 1
	s_cmp_lg_u32 s43, 0
	s_cbranch_scc1 .Lscan2p_blk

; template <int KG> __device__ __forceinline__ float redKG(float x) { x = red8d(x); if (KG == 16) x += dpp_rm(x); return x; }
; template <int MIX, int KPL, int KG>
; __device__ __forceinline__ float do_step(const StepIn<MIX, KPL>& s, float (&S)[KPL], const float gam) {
;     ...
;   } else {
;     float o0 = 0.f, o1 = 0.f;
; #pragma unroll
;     for (int i = 0; i < KPL; i += 2) {
;       const float d0 = (MIX == 3) ? gam : s.d[i], d1 = (MIX == 3) ? gam : s.d[i + 1];
;       S[i] = d0 * S[i] + s.k[i] * s.v; S[i + 1] = d1 * S[i + 1] + s.k[i + 1] * s.v;
;       o0 += s.q[i] * S[i]; o1 += s.q[i + 1] * S[i + 1];
;     }
;     return redKG<KG>(o0 + o1);
;   }
; template <int MIX>
; __device__ __forceinline__ void scan_part(const Params& p, const int layer, const int smp, const int b0, const int bstep, const int bend, const int h, const int part, char* lds, const int tid) {
;     ...
;     {
;       StepIn<MIX, KPL> sa, sb;
;       float osave = 0.f;
;       load_step<MIX, KPL>(qkdv, scal, 0, kg, col, sa);
;       for (int t = 0; t < ntok; t += 2) {
;         load_step<MIX, KPL>(qkdv, scal, t + 1, kg, col, sb);
;         __builtin_amdgcn_sched_barrier(0);
;         const float oa = do_step<MIX, KPL, KG>(sa, S, gam);
;         osave = (kg == (t & (KG - 1))) ? oa : osave;
;         load_step<MIX, KPL>(qkdv, scal, min(t + 2, ntok - 1), kg, col, sa);
;         __builtin_amdgcn_sched_barrier(0);
;         const float ob = do_step<MIX, KPL, KG>(sb, S, gam);
;         osave = (kg == ((t + 1) & (KG - 1))) ? ob : osave;
;         if (((t + 2) & (KG - 1)) == 0) obuf[(t + 2 - KG + kg) * CW + col] = osave;
;       }
;       const int remn = ntok & (KG - 1);
;       if (remn != 0 && kg < remn) obuf[(ntok - remn + kg) * CW + col] = osave;
;     }
.LBB0_394:
	v_mov_b32_e32 v246, v61
	v_mov_b32_e32 v247, v62
	v_and_b32_e32 v248, 4, v57
	s_lshr_b32 s43, s29, 4
	v_lshl_add_u32 v248, v248, 5, v62
	ds_read_b128 v[138:141], v246 offset:256
	ds_read_b128 v[142:145], v246 offset:272
	ds_read_b32 v104, v247 offset:768
	ds_read_b128 v[192:195], v246 offset:512
	ds_read_b128 v[196:199], v246 offset:528
	ds_read_b128 v[72:75], v246
	ds_read_b128 v[76:79], v246 offset:16
	ds_read_b128 v[148:151], v246 offset:1280
	ds_read_b128 v[152:155], v246 offset:1296
	ds_read_b32 v106, v247 offset:1792
	ds_read_b128 v[200:203], v246 offset:1536
	ds_read_b128 v[204:207], v246 offset:1552
	ds_read_b128 v[80:83], v246 offset:1024
	ds_read_b128 v[84:87], v246 offset:1040
.Lscan1p_blk:
	s_waitcnt lgkmcnt(7)
	ds_read_b128 v[174:177], v246 offset:2304
	ds_read_b32 v132, v247 offset:2816
	ds_read_b128 v[208:211], v246 offset:2560
	ds_read_b128 v[178:181], v246 offset:2320
	ds_read_b128 v[88:91], v246 offset:2048
	ds_read_b128 v[212:215], v246 offset:2576
	ds_read_b128 v[184:187], v246 offset:3328
	ds_read_b32 v134, v247 offset:3840
	ds_read_b128 v[92:95], v246 offset:2064
	v_pk_mul_f32 v[158:159], v[138:139], v[104:105] op_sel_hi:[1,0]
	ds_read_b128 v[216:219], v246 offset:3584
	v_pk_mul_f32 v[168:169], v[140:141], v[104:105] op_sel_hi:[1,0]
	v_pk_fma_f32 v[42:43], v[42:43], v[192:193], v[158:159]
	ds_read_b128 v[188:191], v246 offset:3344
	ds_read_b128 v[96:99], v246 offset:3072
	v_pk_mul_f32 v[224:225], v[142:143], v[104:105] op_sel_hi:[1,0]
	v_pk_fma_f32 v[50:51], v[50:51], v[194:195], v[168:169]
	v_pk_mul_f32 v[236:237], v[72:73], v[42:43]
	ds_read_b128 v[220:223], v246 offset:3600
	v_pk_mul_f32 v[226:227], v[144:145], v[104:105] op_sel_hi:[1,0]
	v_pk_fma_f32 v[52:53], v[52:53], v[196:197], v[224:225]
	v_pk_fma_f32 v[236:237], v[74:75], v[50:51], v[236:237]
	ds_read_b128 v[100:103], v246 offset:3088
	s_waitcnt lgkmcnt(4)
	v_pk_mul_f32 v[228:229], v[148:149], v[106:107] op_sel_hi:[1,0]
	v_pk_fma_f32 v[54:55], v[54:55], v[198:199], v[226:227]
	v_pk_fma_f32 v[236:237], v[76:77], v[52:53], v[236:237]
	v_pk_mul_f32 v[230:231], v[150:151], v[106:107] op_sel_hi:[1,0]
	v_pk_fma_f32 v[42:43], v[42:43], v[200:201], v[228:229]
	v_pk_fma_f32 v[236:237], v[78:79], v[54:55], v[236:237]
	v_pk_mul_f32 v[232:233], v[152:153], v[106:107] op_sel_hi:[1,0]
	v_pk_fma_f32 v[50:51], v[50:51], v[202:203], v[230:231]
	v_pk_mul_f32 v[238:239], v[80:81], v[42:43]
	v_add_f32_e32 v131, v236, v237
	v_pk_mul_f32 v[234:235], v[154:155], v[106:107] op_sel_hi:[1,0]
	v_pk_fma_f32 v[52:53], v[52:53], v[204:205], v[232:233]
	v_pk_fma_f32 v[238:239], v[82:83], v[50:51], v[238:239]
	ds_read_b128 v[138:141], v246 offset:4352
	ds_read_b32 v104, v247 offset:4864
	v_pk_fma_f32 v[54:55], v[54:55], v[206:207], v[234:235]
	v_pk_fma_f32 v[238:239], v[84:85], v[52:53], v[238:239]
	ds_read_b128 v[192:195], v246 offset:4608
	v_pk_fma_f32 v[238:239], v[86:87], v[54:55], v[238:239]
	ds_read_b128 v[142:145], v246 offset:4368
	ds_read_b128 v[72:75], v246 offset:4096
	v_add_f32_dpp v131, v131, v131 quad_perm:[1,0,3,2] row_mask:0xf bank_mask:0xf bound_ctrl:1
	v_add_f32_e32 v136, v238, v239
	ds_read_b128 v[196:199], v246 offset:4624
	ds_read_b128 v[148:151], v246 offset:5376
	ds_read_b32 v106, v247 offset:5888
	ds_read_b128 v[76:79], v246 offset:4112
	v_pk_mul_f32 v[158:159], v[174:175], v[132:133] op_sel_hi:[1,0]
	ds_read_b128 v[200:203], v246 offset:5632
	v_pk_mul_f32 v[168:169], v[176:177], v[132:133] op_sel_hi:[1,0]
	v_pk_fma_f32 v[42:43], v[42:43], v[208:209], v[158:159]
	ds_read_b128 v[152:155], v246 offset:5392
	ds_read_b128 v[80:83], v246 offset:5120
	v_add_f32_dpp v131, v131, v131 quad_perm:[2,3,0,1] row_mask:0xf bank_mask:0xf bound_ctrl:1
	v_add_f32_dpp v136, v136, v136 quad_perm:[1,0,3,2] row_mask:0xf bank_mask:0xf bound_ctrl:1
	v_pk_mul_f32 v[224:225], v[178:179], v[132:133] op_sel_hi:[1,0]
	v_pk_fma_f32 v[50:51], v[50:51], v[210:211], v[168:169]
	v_pk_mul_f32 v[236:237], v[88:89], v[42:43]
	ds_read_b128 v[204:207], v246 offset:5648
	v_pk_mul_f32 v[226:227], v[180:181], v[132:133] op_sel_hi:[1,0]
	v_pk_fma_f32 v[52:53], v[52:53], v[212:213], v[224:225]
	v_pk_fma_f32 v[236:237], v[90:91], v[50:51], v[236:237]
	ds_read_b128 v[84:87], v246 offset:5136
	v_pk_mul_f32 v[228:229], v[184:185], v[134:135] op_sel_hi:[1,0]
	v_pk_fma_f32 v[54:55], v[54:55], v[214:215], v[226:227]
	v_pk_fma_f32 v[236:237], v[92:93], v[52:53], v[236:237]
	v_pk_mul_f32 v[230:231], v[186:187], v[134:135] op_sel_hi:[1,0]
	v_pk_fma_f32 v[42:43], v[42:43], v[216:217], v[228:229]
	v_add_f32_dpp v146, v131, v131 row_half_mirror row_mask:0xf bank_mask:0x5
	v_add_f32_dpp v136, v136, v136 quad_perm:[2,3,0,1] row_mask:0xf bank_mask:0xf bound_ctrl:1
	v_pk_fma_f32 v[236:237], v[94:95], v[54:55], v[236:237]
	s_waitcnt lgkmcnt(1)
; template <int KG> __device__ __forceinline__ float redKG(float x) { x = red8d(x); if (KG == 16) x += dpp_rm(x); return x; }
; template <int MIX, int KPL, int KG>
; __device__ __forceinline__ float do_step(const StepIn<MIX, KPL>& s, float (&S)[KPL], const float gam) {
;     ...
;   } else {
;     float o0 = 0.f, o1 = 0.f;
; #pragma unroll
;     for (int i = 0; i < KPL; i += 2) {
;       const float d0 = (MIX == 3) ? gam : s.d[i], d1 = (MIX == 3) ? gam : s.d[i + 1];
;       S[i] = d0 * S[i] + s.k[i] * s.v; S[i + 1] = d1 * S[i + 1] + s.k[i + 1] * s.v;
;       o0 += s.q[i] * S[i]; o1 += s.q[i + 1] * S[i + 1];
;     }
;     return redKG<KG>(o0 + o1);
;   }
; template <int MIX>
; __device__ __forceinline__ void scan_part(const Params& p, const int layer, const int smp, const int b0, const int bstep, const int bend, const int h, const int part, char* lds, const int tid) {
;     ...
;     {
;       StepIn<MIX, KPL> sa, sb;
;       float osave = 0.f;
;       load_step<MIX, KPL>(qkdv, scal, 0, kg, col, sa);
;       for (int t = 0; t < ntok; t += 2) {
;         load_step<MIX, KPL>(qkdv, scal, t + 1, kg, col, sb);
;         __builtin_amdgcn_sched_barrier(0);
;         const float oa = do_step<MIX, KPL, KG>(sa, S, gam);
;         osave = (kg == (t & (KG - 1))) ? oa : osave;
;         load_step<MIX, KPL>(qkdv, scal, min(t + 2, ntok - 1), kg, col, sa);
;         __builtin_amdgcn_sched_barrier(0);
;         const float ob = do_step<MIX, KPL, KG>(sb, S, gam);
;         osave = (kg == ((t + 1) & (KG - 1))) ? ob : osave;
;         if (((t + 2) & (KG - 1)) == 0) obuf[(t + 2 - KG + kg) * CW + col] = osave;
;       }
;       const int remn = ntok & (KG - 1);
;       if (remn != 0 && kg < remn) obuf[(ntok - remn + kg) * CW + col] = osave;
;     }
	v_pk_mul_f32 v[232:233], v[188:189], v[134:135] op_sel_hi:[1,0]
	v_pk_fma_f32 v[50:51], v[50:51], v[218:219], v[230:231]
	v_pk_mul_f32 v[238:239], v[96:97], v[42:43]
	v_add_f32_e32 v131, v236, v237
	v_pk_mul_f32 v[234:235], v[190:191], v[134:135] op_sel_hi:[1,0]
	v_pk_fma_f32 v[52:53], v[52:53], v[220:221], v[232:233]
	v_pk_fma_f32 v[238:239], v[98:99], v[50:51], v[238:239]
	ds_read_b128 v[174:177], v246 offset:6400
	ds_read_b32 v132, v247 offset:6912
	v_pk_fma_f32 v[54:55], v[54:55], v[222:223], v[234:235]
	v_pk_fma_f32 v[238:239], v[100:101], v[52:53], v[238:239]
	ds_read_b128 v[208:211], v246 offset:6656
	v_add_f32_dpp v146, v136, v136 row_half_mirror row_mask:0xf bank_mask:0xa
	v_pk_fma_f32 v[238:239], v[102:103], v[54:55], v[238:239]
	ds_read_b128 v[178:181], v246 offset:6416
	ds_read_b128 v[88:91], v246 offset:6144
	v_add_f32_dpp v131, v131, v131 quad_perm:[1,0,3,2] row_mask:0xf bank_mask:0xf bound_ctrl:1
	v_add_f32_e32 v136, v238, v239
	ds_read_b128 v[212:215], v246 offset:6672
	ds_read_b128 v[184:187], v246 offset:7424
	ds_read_b32 v134, v247 offset:7936
	ds_read_b128 v[92:95], v246 offset:6160
	v_pk_mul_f32 v[158:159], v[138:139], v[104:105] op_sel_hi:[1,0]
	ds_read_b128 v[216:219], v246 offset:7680
	v_pk_mul_f32 v[168:169], v[140:141], v[104:105] op_sel_hi:[1,0]
	v_pk_fma_f32 v[42:43], v[42:43], v[192:193], v[158:159]
	ds_read_b128 v[188:191], v246 offset:7440
	ds_read_b128 v[96:99], v246 offset:7168
	v_add_f32_dpp v131, v131, v131 quad_perm:[2,3,0,1] row_mask:0xf bank_mask:0xf bound_ctrl:1
	v_add_f32_dpp v136, v136, v136 quad_perm:[1,0,3,2] row_mask:0xf bank_mask:0xf bound_ctrl:1
	v_pk_mul_f32 v[224:225], v[142:143], v[104:105] op_sel_hi:[1,0]
	v_pk_fma_f32 v[50:51], v[50:51], v[194:195], v[168:169]
	v_pk_mul_f32 v[236:237], v[72:73], v[42:43]
	ds_read_b128 v[220:223], v246 offset:7696
	v_pk_mul_f32 v[226:227], v[144:145], v[104:105] op_sel_hi:[1,0]
	v_pk_fma_f32 v[52:53], v[52:53], v[196:197], v[224:225]
	v_pk_fma_f32 v[236:237], v[74:75], v[50:51], v[236:237]
	ds_read_b128 v[100:103], v246 offset:7184
	v_pk_mul_f32 v[228:229], v[148:149], v[106:107] op_sel_hi:[1,0]
	v_pk_fma_f32 v[54:55], v[54:55], v[198:199], v[226:227]
	v_pk_fma_f32 v[236:237], v[76:77], v[52:53], v[236:237]
	v_pk_mul_f32 v[230:231], v[150:151], v[106:107] op_sel_hi:[1,0]
	v_pk_fma_f32 v[42:43], v[42:43], v[200:201], v[228:229]
	v_add_f32_dpp v182, v131, v131 row_half_mirror row_mask:0xf bank_mask:0x5
	v_add_f32_dpp v136, v136, v136 quad_perm:[2,3,0,1] row_mask:0xf bank_mask:0xf bound_ctrl:1
	v_pk_fma_f32 v[236:237], v[78:79], v[54:55], v[236:237]
	v_pk_mul_f32 v[232:233], v[152:153], v[106:107] op_sel_hi:[1,0]
	v_pk_fma_f32 v[50:51], v[50:51], v[202:203], v[230:231]
	v_pk_mul_f32 v[238:239], v[80:81], v[42:43]
	v_add_f32_e32 v131, v236, v237
	v_pk_mul_f32 v[234:235], v[154:155], v[106:107] op_sel_hi:[1,0]
	v_pk_fma_f32 v[52:53], v[52:53], v[204:205], v[232:233]
	v_pk_fma_f32 v[238:239], v[82:83], v[50:51], v[238:239]
	ds_read_b128 v[138:141], v246 offset:8448
	ds_read_b32 v104, v247 offset:8960
	v_pk_fma_f32 v[54:55], v[54:55], v[206:207], v[234:235]
	s_waitcnt lgkmcnt(2)
	v_pk_fma_f32 v[238:239], v[84:85], v[52:53], v[238:239]
	ds_read_b128 v[192:195], v246 offset:8704
	v_add_f32_dpp v182, v136, v136 row_half_mirror row_mask:0xf bank_mask:0xa
	v_pk_fma_f32 v[238:239], v[86:87], v[54:55], v[238:239]
	ds_read_b128 v[142:145], v246 offset:8464
	ds_read_b128 v[72:75], v246 offset:8192
	v_add_f32_dpp v131, v131, v131 quad_perm:[1,0,3,2] row_mask:0xf bank_mask:0xf bound_ctrl:1
	v_add_f32_e32 v136, v238, v239
	ds_read_b128 v[196:199], v246 offset:8720
	ds_read_b128 v[148:151], v246 offset:9472
	ds_read_b32 v106, v247 offset:9984
	ds_read_b128 v[76:79], v246 offset:8208
	v_pk_mul_f32 v[158:159], v[174:175], v[132:133] op_sel_hi:[1,0]
	ds_read_b128 v[200:203], v246 offset:9728
	v_pk_mul_f32 v[168:169], v[176:177], v[132:133] op_sel_hi:[1,0]
	v_pk_fma_f32 v[42:43], v[42:43], v[208:209], v[158:159]
	ds_read_b128 v[152:155], v246 offset:9488
	ds_read_b128 v[80:83], v246 offset:9216
	v_add_f32_dpp v131, v131, v131 quad_perm:[2,3,0,1] row_mask:0xf bank_mask:0xf bound_ctrl:1
	v_add_f32_dpp v136, v136, v136 quad_perm:[1,0,3,2] row_mask:0xf bank_mask:0xf bound_ctrl:1
	v_pk_mul_f32 v[224:225], v[178:179], v[132:133] op_sel_hi:[1,0]
	v_pk_fma_f32 v[50:51], v[50:51], v[210:211], v[168:169]
	v_pk_mul_f32 v[236:237], v[88:89], v[42:43]
	ds_read_b128 v[204:207], v246 offset:9744
	v_pk_mul_f32 v[226:227], v[180:181], v[132:133] op_sel_hi:[1,0]
	v_pk_fma_f32 v[52:53], v[52:53], v[212:213], v[224:225]
	v_pk_fma_f32 v[236:237], v[90:91], v[50:51], v[236:237]
	ds_read_b128 v[84:87], v246 offset:9232
	v_pk_mul_f32 v[228:229], v[184:185], v[134:135] op_sel_hi:[1,0]
	v_pk_fma_f32 v[54:55], v[54:55], v[214:215], v[226:227]
	v_pk_fma_f32 v[236:237], v[92:93], v[52:53], v[236:237]
	v_pk_mul_f32 v[230:231], v[186:187], v[134:135] op_sel_hi:[1,0]
	v_pk_fma_f32 v[42:43], v[42:43], v[216:217], v[228:229]
	v_add_f32_dpp v240, v131, v131 row_half_mirror row_mask:0xf bank_mask:0x5
	v_add_f32_dpp v136, v136, v136 quad_perm:[2,3,0,1] row_mask:0xf bank_mask:0xf bound_ctrl:1
	v_pk_fma_f32 v[236:237], v[94:95], v[54:55], v[236:237]
	v_pk_mul_f32 v[232:233], v[188:189], v[134:135] op_sel_hi:[1,0]
	v_pk_fma_f32 v[50:51], v[50:51], v[218:219], v[230:231]
	v_pk_mul_f32 v[238:239], v[96:97], v[42:43]
	v_add_f32_e32 v131, v236, v237
	v_pk_mul_f32 v[234:235], v[190:191], v[134:135] op_sel_hi:[1,0]
	v_pk_fma_f32 v[52:53], v[52:53], v[220:221], v[232:233]
	v_pk_fma_f32 v[238:239], v[98:99], v[50:51], v[238:239]
	ds_read_b128 v[174:177], v246 offset:10496
	ds_read_b32 v132, v247 offset:11008
	v_pk_fma_f32 v[54:55], v[54:55], v[222:223], v[234:235]
	v_pk_fma_f32 v[238:239], v[100:101], v[52:53], v[238:239]
	ds_read_b128 v[208:211], v246 offset:10752
	v_add_f32_dpp v240, v136, v136 row_half_mirror row_mask:0xf bank_mask:0xa
	v_pk_fma_f32 v[238:239], v[102:103], v[54:55], v[238:239]
	ds_read_b128 v[178:181], v246 offset:10512
	ds_read_b128 v[88:91], v246 offset:10240
	v_add_f32_dpp v131, v131, v131 quad_perm:[1,0,3,2] row_mask:0xf bank_mask:0xf bound_ctrl:1
	v_add_f32_e32 v136, v238, v239
	ds_read_b128 v[212:215], v246 offset:10768
	ds_read_b128 v[184:187], v246 offset:11520
	ds_read_b32 v134, v247 offset:12032
	ds_read_b128 v[92:95], v246 offset:10256
	s_waitcnt lgkmcnt(7)
; template <int KG> __device__ __forceinline__ float redKG(float x) { x = red8d(x); if (KG == 16) x += dpp_rm(x); return x; }
; template <int MIX, int KPL, int KG>
; __device__ __forceinline__ float do_step(const StepIn<MIX, KPL>& s, float (&S)[KPL], const float gam) {
;     ...
;   } else {
;     float o0 = 0.f, o1 = 0.f;
; #pragma unroll
;     for (int i = 0; i < KPL; i += 2) {
;       const float d0 = (MIX == 3) ? gam : s.d[i], d1 = (MIX == 3) ? gam : s.d[i + 1];
;       S[i] = d0 * S[i] + s.k[i] * s.v; S[i + 1] = d1 * S[i + 1] + s.k[i + 1] * s.v;
;       o0 += s.q[i] * S[i]; o1 += s.q[i + 1] * S[i + 1];
;     }
;     return redKG<KG>(o0 + o1);
;   }
; template <int MIX>
; __device__ __forceinline__ void scan_part(const Params& p, const int layer, const int smp, const int b0, const int bstep, const int bend, const int h, const int part, char* lds, const int tid) {
;     ...
;     {
;       StepIn<MIX, KPL> sa, sb;
;       float osave = 0.f;
;       load_step<MIX, KPL>(qkdv, scal, 0, kg, col, sa);
;       for (int t = 0; t < ntok; t += 2) {
;         load_step<MIX, KPL>(qkdv, scal, t + 1, kg, col, sb);
;         __builtin_amdgcn_sched_barrier(0);
;         const float oa = do_step<MIX, KPL, KG>(sa, S, gam);
;         osave = (kg == (t & (KG - 1))) ? oa : osave;
;         load_step<MIX, KPL>(qkdv, scal, min(t + 2, ntok - 1), kg, col, sa);
;         __builtin_amdgcn_sched_barrier(0);
;         const float ob = do_step<MIX, KPL, KG>(sb, S, gam);
;         osave = (kg == ((t + 1) & (KG - 1))) ? ob : osave;
;         if (((t + 2) & (KG - 1)) == 0) obuf[(t + 2 - KG + kg) * CW + col] = osave;
;       }
;       const int remn = ntok & (KG - 1);
;       if (remn != 0 && kg < remn) obuf[(ntok - remn + kg) * CW + col] = osave;
;     }
	v_pk_mul_f32 v[158:159], v[138:139], v[104:105] op_sel_hi:[1,0]
	ds_read_b128 v[216:219], v246 offset:11776
	v_pk_mul_f32 v[168:169], v[140:141], v[104:105] op_sel_hi:[1,0]
	v_pk_fma_f32 v[42:43], v[42:43], v[192:193], v[158:159]
	ds_read_b128 v[188:191], v246 offset:11536
	ds_read_b128 v[96:99], v246 offset:11264
	v_add_f32_dpp v131, v131, v131 quad_perm:[2,3,0,1] row_mask:0xf bank_mask:0xf bound_ctrl:1
	v_add_f32_dpp v136, v136, v136 quad_perm:[1,0,3,2] row_mask:0xf bank_mask:0xf bound_ctrl:1
	v_pk_mul_f32 v[224:225], v[142:143], v[104:105] op_sel_hi:[1,0]
	v_pk_fma_f32 v[50:51], v[50:51], v[194:195], v[168:169]
	v_pk_mul_f32 v[236:237], v[72:73], v[42:43]
	ds_read_b128 v[220:223], v246 offset:11792
	v_pk_mul_f32 v[226:227], v[144:145], v[104:105] op_sel_hi:[1,0]
	v_pk_fma_f32 v[52:53], v[52:53], v[196:197], v[224:225]
	v_pk_fma_f32 v[236:237], v[74:75], v[50:51], v[236:237]
	ds_read_b128 v[100:103], v246 offset:11280
	v_pk_mul_f32 v[228:229], v[148:149], v[106:107] op_sel_hi:[1,0]
	v_pk_fma_f32 v[54:55], v[54:55], v[198:199], v[226:227]
	v_pk_fma_f32 v[236:237], v[76:77], v[52:53], v[236:237]
	v_pk_mul_f32 v[230:231], v[150:151], v[106:107] op_sel_hi:[1,0]
	v_pk_fma_f32 v[42:43], v[42:43], v[200:201], v[228:229]
	v_add_f32_dpp v241, v131, v131 row_half_mirror row_mask:0xf bank_mask:0x5
	v_add_f32_dpp v136, v136, v136 quad_perm:[2,3,0,1] row_mask:0xf bank_mask:0xf bound_ctrl:1
	v_pk_fma_f32 v[236:237], v[78:79], v[54:55], v[236:237]
	v_pk_mul_f32 v[232:233], v[152:153], v[106:107] op_sel_hi:[1,0]
	v_pk_fma_f32 v[50:51], v[50:51], v[202:203], v[230:231]
	v_pk_mul_f32 v[238:239], v[80:81], v[42:43]
	v_add_f32_e32 v131, v236, v237
	v_pk_mul_f32 v[234:235], v[154:155], v[106:107] op_sel_hi:[1,0]
	v_pk_fma_f32 v[52:53], v[52:53], v[204:205], v[232:233]
	v_pk_fma_f32 v[238:239], v[82:83], v[50:51], v[238:239]
	ds_read_b128 v[138:141], v246 offset:12544
	ds_read_b32 v104, v247 offset:13056
	v_pk_fma_f32 v[54:55], v[54:55], v[206:207], v[234:235]
	v_pk_fma_f32 v[238:239], v[84:85], v[52:53], v[238:239]
	ds_read_b128 v[192:195], v246 offset:12800
	v_add_f32_dpp v241, v136, v136 row_half_mirror row_mask:0xf bank_mask:0xa
	v_pk_fma_f32 v[238:239], v[86:87], v[54:55], v[238:239]
	ds_read_b128 v[142:145], v246 offset:12560
	ds_read_b128 v[72:75], v246 offset:12288
	v_add_f32_dpp v131, v131, v131 quad_perm:[1,0,3,2] row_mask:0xf bank_mask:0xf bound_ctrl:1
	v_add_f32_e32 v136, v238, v239
	ds_read_b128 v[196:199], v246 offset:12816
	ds_read_b128 v[148:151], v246 offset:13568
	ds_read_b32 v106, v247 offset:14080
	ds_read_b128 v[76:79], v246 offset:12304
	v_pk_mul_f32 v[158:159], v[174:175], v[132:133] op_sel_hi:[1,0]
	ds_read_b128 v[200:203], v246 offset:13824
	v_pk_mul_f32 v[168:169], v[176:177], v[132:133] op_sel_hi:[1,0]
	s_waitcnt lgkmcnt(7)
	v_pk_fma_f32 v[42:43], v[42:43], v[208:209], v[158:159]
	ds_read_b128 v[152:155], v246 offset:13584
	ds_read_b128 v[80:83], v246 offset:13312
	v_add_f32_dpp v131, v131, v131 quad_perm:[2,3,0,1] row_mask:0xf bank_mask:0xf bound_ctrl:1
	v_add_f32_dpp v136, v136, v136 quad_perm:[1,0,3,2] row_mask:0xf bank_mask:0xf bound_ctrl:1
	v_pk_mul_f32 v[224:225], v[178:179], v[132:133] op_sel_hi:[1,0]
	v_pk_fma_f32 v[50:51], v[50:51], v[210:211], v[168:169]
	v_pk_mul_f32 v[236:237], v[88:89], v[42:43]
	ds_read_b128 v[204:207], v246 offset:13840
	v_pk_mul_f32 v[226:227], v[180:181], v[132:133] op_sel_hi:[1,0]
	v_pk_fma_f32 v[52:53], v[52:53], v[212:213], v[224:225]
	v_pk_fma_f32 v[236:237], v[90:91], v[50:51], v[236:237]
	ds_read_b128 v[84:87], v246 offset:13328
	v_pk_mul_f32 v[228:229], v[184:185], v[134:135] op_sel_hi:[1,0]
	v_pk_fma_f32 v[54:55], v[54:55], v[214:215], v[226:227]
	v_pk_fma_f32 v[236:237], v[92:93], v[52:53], v[236:237]
	v_pk_mul_f32 v[230:231], v[186:187], v[134:135] op_sel_hi:[1,0]
	v_pk_fma_f32 v[42:43], v[42:43], v[216:217], v[228:229]
	v_add_f32_dpp v242, v131, v131 row_half_mirror row_mask:0xf bank_mask:0x5
	v_add_f32_dpp v136, v136, v136 quad_perm:[2,3,0,1] row_mask:0xf bank_mask:0xf bound_ctrl:1
	v_pk_fma_f32 v[236:237], v[94:95], v[54:55], v[236:237]
	v_pk_mul_f32 v[232:233], v[188:189], v[134:135] op_sel_hi:[1,0]
	v_pk_fma_f32 v[50:51], v[50:51], v[218:219], v[230:231]
	v_pk_mul_f32 v[238:239], v[96:97], v[42:43]
	v_add_f32_e32 v131, v236, v237
	v_pk_mul_f32 v[234:235], v[190:191], v[134:135] op_sel_hi:[1,0]
	v_pk_fma_f32 v[52:53], v[52:53], v[220:221], v[232:233]
	v_pk_fma_f32 v[238:239], v[98:99], v[50:51], v[238:239]
	ds_read_b128 v[174:177], v246 offset:14592
	ds_read_b32 v132, v247 offset:15104
	v_pk_fma_f32 v[54:55], v[54:55], v[222:223], v[234:235]
	v_pk_fma_f32 v[238:239], v[100:101], v[52:53], v[238:239]
	ds_read_b128 v[208:211], v246 offset:14848
	v_add_f32_dpp v242, v136, v136 row_half_mirror row_mask:0xf bank_mask:0xa
	v_pk_fma_f32 v[238:239], v[102:103], v[54:55], v[238:239]
	ds_read_b128 v[178:181], v246 offset:14608
	ds_read_b128 v[88:91], v246 offset:14336
	v_add_f32_dpp v131, v131, v131 quad_perm:[1,0,3,2] row_mask:0xf bank_mask:0xf bound_ctrl:1
	v_add_f32_e32 v136, v238, v239
	ds_read_b128 v[212:215], v246 offset:14864
	ds_read_b128 v[184:187], v246 offset:15616
	ds_read_b32 v134, v247 offset:16128
	ds_read_b128 v[92:95], v246 offset:14352
	v_pk_mul_f32 v[158:159], v[138:139], v[104:105] op_sel_hi:[1,0]
	ds_read_b128 v[216:219], v246 offset:15872
	v_pk_mul_f32 v[168:169], v[140:141], v[104:105] op_sel_hi:[1,0]
	v_pk_fma_f32 v[42:43], v[42:43], v[192:193], v[158:159]
	ds_read_b128 v[188:191], v246 offset:15632
	ds_read_b128 v[96:99], v246 offset:15360
	v_add_f32_dpp v131, v131, v131 quad_perm:[2,3,0,1] row_mask:0xf bank_mask:0xf bound_ctrl:1
	v_add_f32_dpp v136, v136, v136 quad_perm:[1,0,3,2] row_mask:0xf bank_mask:0xf bound_ctrl:1
	s_waitcnt lgkmcnt(6)
; template <int KG> __device__ __forceinline__ float redKG(float x) { x = red8d(x); if (KG == 16) x += dpp_rm(x); return x; }
; template <int MIX, int KPL, int KG>
; __device__ __forceinline__ float do_step(const StepIn<MIX, KPL>& s, float (&S)[KPL], const float gam) {
;     ...
;   } else {
;     float o0 = 0.f, o1 = 0.f;
; #pragma unroll
;     for (int i = 0; i < KPL; i += 2) {
;       const float d0 = (MIX == 3) ? gam : s.d[i], d1 = (MIX == 3) ? gam : s.d[i + 1];
;       S[i] = d0 * S[i] + s.k[i] * s.v; S[i + 1] = d1 * S[i + 1] + s.k[i + 1] * s.v;
;       o0 += s.q[i] * S[i]; o1 += s.q[i + 1] * S[i + 1];
;     }
;     return redKG<KG>(o0 + o1);
;   }
; template <int MIX>
; __device__ __forceinline__ void scan_part(const Params& p, const int layer, const int smp, const int b0, const int bstep, const int bend, const int h, const int part, char* lds, const int tid) {
;     ...
;     {
;       StepIn<MIX, KPL> sa, sb;
;       float osave = 0.f;
;       load_step<MIX, KPL>(qkdv, scal, 0, kg, col, sa);
;       for (int t = 0; t < ntok; t += 2) {
;         load_step<MIX, KPL>(qkdv, scal, t + 1, kg, col, sb);
;         __builtin_amdgcn_sched_barrier(0);
;         const float oa = do_step<MIX, KPL, KG>(sa, S, gam);
;         osave = (kg == (t & (KG - 1))) ? oa : osave;
;         load_step<MIX, KPL>(qkdv, scal, min(t + 2, ntok - 1), kg, col, sa);
;         __builtin_amdgcn_sched_barrier(0);
;         const float ob = do_step<MIX, KPL, KG>(sb, S, gam);
;         osave = (kg == ((t + 1) & (KG - 1))) ? ob : osave;
;         if (((t + 2) & (KG - 1)) == 0) obuf[(t + 2 - KG + kg) * CW + col] = osave;
;       }
;       const int remn = ntok & (KG - 1);
;       if (remn != 0 && kg < remn) obuf[(ntok - remn + kg) * CW + col] = osave;
;     }
	v_pk_mul_f32 v[224:225], v[142:143], v[104:105] op_sel_hi:[1,0]
	v_pk_fma_f32 v[50:51], v[50:51], v[194:195], v[168:169]
	v_pk_mul_f32 v[236:237], v[72:73], v[42:43]
	ds_read_b128 v[220:223], v246 offset:15888
	v_pk_mul_f32 v[226:227], v[144:145], v[104:105] op_sel_hi:[1,0]
	v_pk_fma_f32 v[52:53], v[52:53], v[196:197], v[224:225]
	v_pk_fma_f32 v[236:237], v[74:75], v[50:51], v[236:237]
	ds_read_b128 v[100:103], v246 offset:15376
	v_pk_mul_f32 v[228:229], v[148:149], v[106:107] op_sel_hi:[1,0]
	v_pk_fma_f32 v[54:55], v[54:55], v[198:199], v[226:227]
	v_pk_fma_f32 v[236:237], v[76:77], v[52:53], v[236:237]
	v_pk_mul_f32 v[230:231], v[150:151], v[106:107] op_sel_hi:[1,0]
	v_pk_fma_f32 v[42:43], v[42:43], v[200:201], v[228:229]
	v_add_f32_dpp v243, v131, v131 row_half_mirror row_mask:0xf bank_mask:0x5
	v_add_f32_dpp v136, v136, v136 quad_perm:[2,3,0,1] row_mask:0xf bank_mask:0xf bound_ctrl:1
	v_pk_fma_f32 v[236:237], v[78:79], v[54:55], v[236:237]
	v_pk_mul_f32 v[232:233], v[152:153], v[106:107] op_sel_hi:[1,0]
	v_pk_fma_f32 v[50:51], v[50:51], v[202:203], v[230:231]
	v_pk_mul_f32 v[238:239], v[80:81], v[42:43]
	v_add_f32_e32 v131, v236, v237
	v_pk_mul_f32 v[234:235], v[154:155], v[106:107] op_sel_hi:[1,0]
	v_pk_fma_f32 v[52:53], v[52:53], v[204:205], v[232:233]
	v_pk_fma_f32 v[238:239], v[82:83], v[50:51], v[238:239]
	v_pk_fma_f32 v[54:55], v[54:55], v[206:207], v[234:235]
	v_pk_fma_f32 v[238:239], v[84:85], v[52:53], v[238:239]
	v_add_f32_dpp v243, v136, v136 row_half_mirror row_mask:0xf bank_mask:0xa
	v_pk_fma_f32 v[238:239], v[86:87], v[54:55], v[238:239]
	v_add_f32_dpp v131, v131, v131 quad_perm:[1,0,3,2] row_mask:0xf bank_mask:0xf bound_ctrl:1
	v_add_f32_e32 v136, v238, v239
	v_pk_mul_f32 v[158:159], v[174:175], v[132:133] op_sel_hi:[1,0]
	v_pk_mul_f32 v[168:169], v[176:177], v[132:133] op_sel_hi:[1,0]
	v_pk_fma_f32 v[42:43], v[42:43], v[208:209], v[158:159]
	v_add_f32_dpp v131, v131, v131 quad_perm:[2,3,0,1] row_mask:0xf bank_mask:0xf bound_ctrl:1
	v_add_f32_dpp v136, v136, v136 quad_perm:[1,0,3,2] row_mask:0xf bank_mask:0xf bound_ctrl:1
	v_pk_mul_f32 v[224:225], v[178:179], v[132:133] op_sel_hi:[1,0]
	v_pk_fma_f32 v[50:51], v[50:51], v[210:211], v[168:169]
	v_pk_mul_f32 v[236:237], v[88:89], v[42:43]
	v_pk_mul_f32 v[226:227], v[180:181], v[132:133] op_sel_hi:[1,0]
	v_pk_fma_f32 v[52:53], v[52:53], v[212:213], v[224:225]
	v_pk_fma_f32 v[236:237], v[90:91], v[50:51], v[236:237]
	s_waitcnt lgkmcnt(0)
	v_pk_mul_f32 v[228:229], v[184:185], v[134:135] op_sel_hi:[1,0]
	v_pk_fma_f32 v[54:55], v[54:55], v[214:215], v[226:227]
	v_pk_fma_f32 v[236:237], v[92:93], v[52:53], v[236:237]
	v_pk_mul_f32 v[230:231], v[186:187], v[134:135] op_sel_hi:[1,0]
	v_pk_fma_f32 v[42:43], v[42:43], v[216:217], v[228:229]
	v_add_f32_dpp v244, v131, v131 row_half_mirror row_mask:0xf bank_mask:0x5
	v_add_f32_dpp v136, v136, v136 quad_perm:[2,3,0,1] row_mask:0xf bank_mask:0xf bound_ctrl:1
	v_pk_fma_f32 v[236:237], v[94:95], v[54:55], v[236:237]
	v_pk_mul_f32 v[232:233], v[188:189], v[134:135] op_sel_hi:[1,0]
	v_pk_fma_f32 v[50:51], v[50:51], v[218:219], v[230:231]
	v_pk_mul_f32 v[238:239], v[96:97], v[42:43]
	v_add_f32_e32 v131, v236, v237
	v_pk_mul_f32 v[234:235], v[190:191], v[134:135] op_sel_hi:[1,0]
	v_pk_fma_f32 v[52:53], v[52:53], v[220:221], v[232:233]
	v_pk_fma_f32 v[238:239], v[98:99], v[50:51], v[238:239]
	v_pk_fma_f32 v[54:55], v[54:55], v[222:223], v[234:235]
	v_pk_fma_f32 v[238:239], v[100:101], v[52:53], v[238:239]
	v_add_f32_dpp v244, v136, v136 row_half_mirror row_mask:0xf bank_mask:0xa
	v_pk_fma_f32 v[238:239], v[102:103], v[54:55], v[238:239]
	v_add_f32_dpp v131, v131, v131 quad_perm:[1,0,3,2] row_mask:0xf bank_mask:0xf bound_ctrl:1
	v_add_f32_e32 v136, v238, v239
	ds_read_b128 v[138:141], v246 offset:16640
	v_add_f32_dpp v131, v131, v131 quad_perm:[2,3,0,1] row_mask:0xf bank_mask:0xf bound_ctrl:1
	v_add_f32_dpp v136, v136, v136 quad_perm:[1,0,3,2] row_mask:0xf bank_mask:0xf bound_ctrl:1
	ds_read_b128 v[142:145], v246 offset:16656
	v_add_f32_dpp v245, v131, v131 row_half_mirror row_mask:0xf bank_mask:0x5
	v_add_f32_dpp v136, v136, v136 quad_perm:[2,3,0,1] row_mask:0xf bank_mask:0xf bound_ctrl:1
	ds_read_b32 v104, v247 offset:17152
	ds_read_b128 v[192:195], v246 offset:16896
	v_add_f32_dpp v245, v136, v136 row_half_mirror row_mask:0xf bank_mask:0xa
	ds_read_b128 v[196:199], v246 offset:16912
	ds_read_b128 v[72:75], v246 offset:16384
	ds_read_b128 v[76:79], v246 offset:16400
	ds_read_b128 v[148:151], v246 offset:17664
	ds_read_b128 v[152:155], v246 offset:17680
	ds_read_b32 v106, v247 offset:18176
	ds_read_b128 v[200:203], v246 offset:17920
	ds_read_b128 v[204:207], v246 offset:17936
	ds_read_b128 v[80:83], v246 offset:17408
	ds_read_b128 v[84:87], v246 offset:17424
	ds_write_b32 v248, v146 offset:32768
	ds_write_b32 v248, v182 offset:33024
	ds_write_b32 v248, v240 offset:33280
	ds_write_b32 v248, v241 offset:33536
	ds_write_b32 v248, v242 offset:33792
	ds_write_b32 v248, v243 offset:34048
	ds_write_b32 v248, v244 offset:34304
	ds_write_b32 v248, v245 offset:34560
	v_add_u32_e32 v246, 0x4000, v246
	v_add_u32_e32 v247, 0x4000, v247
	v_add_u32_e32 v248, 0x800, v248
	s_sub_i32 s43, s43, 1
	s_cmp_lg_u32 s43, 0
	s_cbranch_scc1 .Lscan1p_blk

; template <int KG> __device__ __forceinline__ float redKG(float x) { x = red8d(x); if (KG == 16) x += dpp_rm(x); return x; }
; template <int MIX, int KPL, int KG>
; __device__ __forceinline__ float do_step(const StepIn<MIX, KPL>& s, float (&S)[KPL], const float gam) {
;   if (MIX == 0) {
;     float kS0 = 0.f, kS1 = 0.f, qS0 = 0.f, qS1 = 0.f;
; #pragma unroll
;     for (int i = 0; i < KPL; i += 2) { kS0 += s.k[i] * S[i]; kS1 += s.k[i + 1] * S[i + 1]; qS0 += s.q[i] * S[i]; qS1 += s.q[i + 1] * S[i + 1]; }
;     const float kS = redKG<KG>(kS0 + kS1), qS = redKG<KG>(qS0 + qS1);
;     const float w = s.be * (s.v - s.a * kS);
; #pragma unroll
;     for (int i = 0; i < KPL; ++i) S[i] = s.a * S[i] + s.k[i] * w;
;     return s.a * qS + s.qk * w;
; template <int MIX>
; __device__ __forceinline__ void scan_part(const Params& p, const int layer, const int smp, const int b0, const int bstep, const int bend, const int h, const int part, char* lds, const int tid) {
;     ...
;     {
;       StepIn<MIX, KPL> sa, sb;
;       float osave = 0.f;
;       load_step<MIX, KPL>(qkdv, scal, 0, kg, col, sa);
;       for (int t = 0; t < ntok; t += 2) {
;         load_step<MIX, KPL>(qkdv, scal, t + 1, kg, col, sb);
;         __builtin_amdgcn_sched_barrier(0);
;         const float oa = do_step<MIX, KPL, KG>(sa, S, gam);
;         osave = (kg == (t & (KG - 1))) ? oa : osave;
;         load_step<MIX, KPL>(qkdv, scal, min(t + 2, ntok - 1), kg, col, sa);
;         __builtin_amdgcn_sched_barrier(0);
;         const float ob = do_step<MIX, KPL, KG>(sb, S, gam);
;         osave = (kg == ((t + 1) & (KG - 1))) ? ob : osave;
;         if (((t + 2) & (KG - 1)) == 0) obuf[(t + 2 - KG + kg) * CW + col] = osave;
;       }
;       const int remn = ntok & (KG - 1);
;       if (remn != 0 && kg < remn) obuf[(ntok - remn + kg) * CW + col] = osave;
;     }
.LBB0_432:
	v_mov_b32_e32 v217, v145
	v_mov_b32_e32 v218, v136
	v_mov_b32_e32 v219, 0
	v_and_b32_e32 v220, 12, v135
	s_lshr_b32 s50, s26, 4
	v_lshl_add_u32 v220, v220, 6, v136
	ds_read_b128 v[92:95], v217 offset:256
	ds_read_b128 v[188:191], v219 offset:36864
	ds_read_b32 v0, v218 offset:768
	ds_read_b128 v[76:79], v217
	ds_read_b128 v[174:177], v217 offset:1280
	ds_read_b128 v[192:195], v219 offset:36880
	ds_read_b32 v1, v218 offset:1792
	ds_read_b128 v[80:83], v217 offset:1024
.Lscan0p_blk:
	s_waitcnt lgkmcnt(4)
	v_pk_mul_f32 v[154:155], v[92:93], v[104:105]
	v_pk_fma_f32 v[154:155], v[94:95], v[102:103], v[154:155]
	v_add_f32_e32 v209, v154, v155
	v_pk_mul_f32 v[158:159], v[104:105], v[188:189] op_sel_hi:[1,0]
	v_pk_mul_f32 v[168:169], v[102:103], v[188:189] op_sel_hi:[1,0]
	v_add_f32_dpp v209, v209, v209 quad_perm:[1,0,3,2] row_mask:0xf bank_mask:0xf bound_ctrl:1
	ds_read_b128 v[178:181], v217 offset:2304
	ds_read_b128 v[196:199], v219 offset:36896
	v_add_f32_dpp v209, v209, v209 quad_perm:[2,3,0,1] row_mask:0xf bank_mask:0xf bound_ctrl:1
	ds_read_b32 v106, v218 offset:2816
	ds_read_b128 v[184:187], v217 offset:3328
	v_add_f32_dpp v209, v209, v209 row_half_mirror row_mask:0xf bank_mask:0xf bound_ctrl:1
	ds_read_b128 v[200:203], v219 offset:36912
	ds_read_b32 v107, v218 offset:3840
	v_add_f32_dpp v209, v209, v209 row_mirror row_mask:0xf bank_mask:0xf bound_ctrl:1
	v_fma_f32 v210, -v188, v209, v0
	v_mul_f32_e32 v212, v189, v210
	v_pk_fma_f32 v[104:105], v[92:93], v[212:213], v[158:159] op_sel_hi:[1,0,1]
	v_pk_fma_f32 v[102:103], v[94:95], v[212:213], v[168:169] op_sel_hi:[1,0,1]
	s_waitcnt lgkmcnt(4)
	v_pk_mul_f32 v[154:155], v[174:175], v[104:105]
	v_pk_fma_f32 v[154:155], v[176:177], v[102:103], v[154:155]
	v_add_f32_e32 v209, v154, v155
	v_pk_mul_f32 v[204:205], v[76:77], v[104:105]
	v_pk_mul_f32 v[158:159], v[104:105], v[192:193] op_sel_hi:[1,0]
	v_add_f32_dpp v209, v209, v209 quad_perm:[1,0,3,2] row_mask:0xf bank_mask:0xf bound_ctrl:1
	v_pk_fma_f32 v[204:205], v[78:79], v[102:103], v[204:205]
	v_pk_mul_f32 v[168:169], v[102:103], v[192:193] op_sel_hi:[1,0]
	v_add_f32_dpp v209, v209, v209 quad_perm:[2,3,0,1] row_mask:0xf bank_mask:0xf bound_ctrl:1
	ds_read_b128 v[84:87], v217 offset:2048
	ds_read_b128 v[92:95], v217 offset:4352
	v_add_f32_dpp v209, v209, v209 row_half_mirror row_mask:0xf bank_mask:0xf bound_ctrl:1
	v_add_f32_e32 v182, v204, v205
	ds_read_b128 v[188:191], v219 offset:36928
	v_add_f32_dpp v209, v209, v209 row_mirror row_mask:0xf bank_mask:0xf bound_ctrl:1
	v_fma_f32 v210, -v192, v209, v1
	v_mul_f32_e32 v212, v193, v210
	v_pk_fma_f32 v[104:105], v[174:175], v[212:213], v[158:159] op_sel_hi:[1,0,1]
	v_pk_fma_f32 v[102:103], v[176:177], v[212:213], v[168:169] op_sel_hi:[1,0,1]
	v_pk_mul_f32 v[154:155], v[178:179], v[104:105]
	v_pk_fma_f32 v[154:155], v[180:181], v[102:103], v[154:155]
	v_add_f32_e32 v209, v154, v155
	v_pk_mul_f32 v[206:207], v[80:81], v[104:105]
	v_pk_mul_f32 v[158:159], v[104:105], v[196:197] op_sel_hi:[1,0]
	v_add_f32_dpp v209, v209, v209 quad_perm:[1,0,3,2] row_mask:0xf bank_mask:0xf bound_ctrl:1
	v_pk_fma_f32 v[206:207], v[82:83], v[102:103], v[206:207]
	v_pk_mul_f32 v[168:169], v[102:103], v[196:197] op_sel_hi:[1,0]
	v_add_f32_dpp v209, v209, v209 quad_perm:[2,3,0,1] row_mask:0xf bank_mask:0xf bound_ctrl:1
	ds_read_b32 v0, v218 offset:4864
	ds_read_b128 v[88:91], v217 offset:3072
	v_add_f32_dpp v209, v209, v209 row_half_mirror row_mask:0xf bank_mask:0xf bound_ctrl:1
	ds_read_b128 v[174:177], v217 offset:5376
	v_add_f32_e32 v208, v206, v207
	v_add_f32_dpp v209, v209, v209 row_mirror row_mask:0xf bank_mask:0xf bound_ctrl:1
	s_waitcnt lgkmcnt(3)
	v_fma_f32 v210, -v196, v209, v106
	v_mul_f32_e32 v212, v197, v210
	v_pk_fma_f32 v[104:105], v[178:179], v[212:213], v[158:159] op_sel_hi:[1,0,1]
	v_pk_fma_f32 v[102:103], v[180:181], v[212:213], v[168:169] op_sel_hi:[1,0,1]
	v_pk_mul_f32 v[154:155], v[184:185], v[104:105]
	v_pk_fma_f32 v[154:155], v[186:187], v[102:103], v[154:155]
	v_add_f32_e32 v209, v154, v155
	v_pk_mul_f32 v[204:205], v[84:85], v[104:105]
	v_pk_mul_f32 v[158:159], v[104:105], v[200:201] op_sel_hi:[1,0]
	v_add_f32_dpp v209, v209, v209 quad_perm:[1,0,3,2] row_mask:0xf bank_mask:0xf bound_ctrl:1
	v_pk_fma_f32 v[204:205], v[86:87], v[102:103], v[204:205]
	v_pk_mul_f32 v[168:169], v[102:103], v[200:201] op_sel_hi:[1,0]
	v_add_f32_dpp v209, v209, v209 quad_perm:[2,3,0,1] row_mask:0xf bank_mask:0xf bound_ctrl:1
	ds_read_b128 v[192:195], v219 offset:36944
	ds_read_b32 v1, v218 offset:5888
	v_add_f32_dpp v209, v209, v209 row_half_mirror row_mask:0xf bank_mask:0xf bound_ctrl:1
	ds_read_b128 v[76:79], v217 offset:4096
	ds_read_b128 v[178:181], v217 offset:6400
	v_add_f32_dpp v209, v209, v209 row_mirror row_mask:0xf bank_mask:0xf bound_ctrl:1
	v_fma_f32 v210, -v200, v209, v107
	v_mul_f32_e32 v212, v201, v210
	v_pk_fma_f32 v[104:105], v[184:185], v[212:213], v[158:159] op_sel_hi:[1,0,1]
	v_pk_fma_f32 v[102:103], v[186:187], v[212:213], v[168:169] op_sel_hi:[1,0,1]
	v_pk_mul_f32 v[154:155], v[92:93], v[104:105]
	v_pk_fma_f32 v[154:155], v[94:95], v[102:103], v[154:155]
	v_add_f32_e32 v209, v154, v155
	s_waitcnt lgkmcnt(2)
; template <int KG> __device__ __forceinline__ float redKG(float x) { x = red8d(x); if (KG == 16) x += dpp_rm(x); return x; }
; template <int MIX, int KPL, int KG>
; __device__ __forceinline__ float do_step(const StepIn<MIX, KPL>& s, float (&S)[KPL], const float gam) {
;   if (MIX == 0) {
;     float kS0 = 0.f, kS1 = 0.f, qS0 = 0.f, qS1 = 0.f;
; #pragma unroll
;     for (int i = 0; i < KPL; i += 2) { kS0 += s.k[i] * S[i]; kS1 += s.k[i + 1] * S[i + 1]; qS0 += s.q[i] * S[i]; qS1 += s.q[i + 1] * S[i + 1]; }
;     const float kS = redKG<KG>(kS0 + kS1), qS = redKG<KG>(qS0 + qS1);
;     const float w = s.be * (s.v - s.a * kS);
; #pragma unroll
;     for (int i = 0; i < KPL; ++i) S[i] = s.a * S[i] + s.k[i] * w;
;     return s.a * qS + s.qk * w;
; template <int MIX>
; __device__ __forceinline__ void scan_part(const Params& p, const int layer, const int smp, const int b0, const int bstep, const int bend, const int h, const int part, char* lds, const int tid) {
;     ...
;     {
;       StepIn<MIX, KPL> sa, sb;
;       float osave = 0.f;
;       load_step<MIX, KPL>(qkdv, scal, 0, kg, col, sa);
;       for (int t = 0; t < ntok; t += 2) {
;         load_step<MIX, KPL>(qkdv, scal, t + 1, kg, col, sb);
;         __builtin_amdgcn_sched_barrier(0);
;         const float oa = do_step<MIX, KPL, KG>(sa, S, gam);
;         osave = (kg == (t & (KG - 1))) ? oa : osave;
;         load_step<MIX, KPL>(qkdv, scal, min(t + 2, ntok - 1), kg, col, sa);
;         __builtin_amdgcn_sched_barrier(0);
;         const float ob = do_step<MIX, KPL, KG>(sb, S, gam);
;         osave = (kg == ((t + 1) & (KG - 1))) ? ob : osave;
;         if (((t + 2) & (KG - 1)) == 0) obuf[(t + 2 - KG + kg) * CW + col] = osave;
;       }
;       const int remn = ntok & (KG - 1);
;       if (remn != 0 && kg < remn) obuf[(ntok - remn + kg) * CW + col] = osave;
;     }
	v_pk_mul_f32 v[206:207], v[88:89], v[104:105]
	v_pk_mul_f32 v[158:159], v[104:105], v[188:189] op_sel_hi:[1,0]
	v_add_f32_dpp v209, v209, v209 quad_perm:[1,0,3,2] row_mask:0xf bank_mask:0xf bound_ctrl:1
	v_pk_fma_f32 v[206:207], v[90:91], v[102:103], v[206:207]
	v_pk_mul_f32 v[168:169], v[102:103], v[188:189] op_sel_hi:[1,0]
	v_add_f32_dpp v209, v209, v209 quad_perm:[2,3,0,1] row_mask:0xf bank_mask:0xf bound_ctrl:1
	v_add_f32_dpp v182, v182, v182 quad_perm:[1,0,3,2] row_mask:0xf bank_mask:0xf bound_ctrl:1
	ds_read_b128 v[196:199], v219 offset:36960
	v_add_f32_dpp v209, v209, v209 row_half_mirror row_mask:0xf bank_mask:0xf bound_ctrl:1
	v_add_f32_dpp v182, v182, v182 quad_perm:[2,3,0,1] row_mask:0xf bank_mask:0xf bound_ctrl:1
	ds_read_b32 v106, v218 offset:6912
	v_add_f32_dpp v209, v209, v209 row_mirror row_mask:0xf bank_mask:0xf bound_ctrl:1
	v_fma_f32 v210, -v188, v209, v0
	v_mul_f32_e32 v212, v189, v210
	v_pk_fma_f32 v[104:105], v[92:93], v[212:213], v[158:159] op_sel_hi:[1,0,1]
	v_pk_fma_f32 v[102:103], v[94:95], v[212:213], v[168:169] op_sel_hi:[1,0,1]
	v_pk_mul_f32 v[154:155], v[174:175], v[104:105]
	v_pk_fma_f32 v[154:155], v[176:177], v[102:103], v[154:155]
	v_add_f32_e32 v209, v154, v155
	v_add_f32_dpp v182, v182, v182 row_half_mirror row_mask:0xf bank_mask:0xf bound_ctrl:1
	v_pk_mul_f32 v[158:159], v[104:105], v[192:193] op_sel_hi:[1,0]
	v_add_f32_dpp v209, v209, v209 quad_perm:[1,0,3,2] row_mask:0xf bank_mask:0xf bound_ctrl:1
	v_add_f32_dpp v211, v182, v182 row_mirror row_mask:0xf bank_mask:0x1
	v_add_f32_e32 v182, v204, v205
	v_add_f32_dpp v209, v209, v209 quad_perm:[2,3,0,1] row_mask:0xf bank_mask:0xf bound_ctrl:1
	s_waitcnt lgkmcnt(0)
	v_pk_mul_f32 v[204:205], v[76:77], v[104:105]
	v_pk_fma_f32 v[204:205], v[78:79], v[102:103], v[204:205]
	v_add_f32_dpp v209, v209, v209 row_half_mirror row_mask:0xf bank_mask:0xf bound_ctrl:1
	v_pk_mul_f32 v[168:169], v[102:103], v[192:193] op_sel_hi:[1,0]
	ds_read_b128 v[80:83], v217 offset:5120
	v_add_f32_dpp v209, v209, v209 row_mirror row_mask:0xf bank_mask:0xf bound_ctrl:1
	v_fma_f32 v210, -v192, v209, v1
	v_mul_f32_e32 v212, v193, v210
	v_pk_fma_f32 v[104:105], v[174:175], v[212:213], v[158:159] op_sel_hi:[1,0,1]
	v_pk_fma_f32 v[102:103], v[176:177], v[212:213], v[168:169] op_sel_hi:[1,0,1]
	v_pk_mul_f32 v[154:155], v[178:179], v[104:105]
	v_pk_fma_f32 v[154:155], v[180:181], v[102:103], v[154:155]
	v_add_f32_e32 v209, v154, v155
	ds_read_b128 v[184:187], v217 offset:7424
	v_add_f32_dpp v208, v208, v208 quad_perm:[1,0,3,2] row_mask:0xf bank_mask:0xf bound_ctrl:1
	v_add_f32_dpp v209, v209, v209 quad_perm:[1,0,3,2] row_mask:0xf bank_mask:0xf bound_ctrl:1
	v_pk_mul_f32 v[158:159], v[104:105], v[196:197] op_sel_hi:[1,0]
	v_add_f32_dpp v208, v208, v208 quad_perm:[2,3,0,1] row_mask:0xf bank_mask:0xf bound_ctrl:1
	v_add_f32_dpp v209, v209, v209 quad_perm:[2,3,0,1] row_mask:0xf bank_mask:0xf bound_ctrl:1
	v_pk_mul_f32 v[168:169], v[102:103], v[196:197] op_sel_hi:[1,0]
	v_add_f32_dpp v208, v208, v208 row_half_mirror row_mask:0xf bank_mask:0xf bound_ctrl:1
	v_add_f32_dpp v209, v209, v209 row_half_mirror row_mask:0xf bank_mask:0xf bound_ctrl:1
	ds_read_b128 v[200:203], v219 offset:36976
	v_add_f32_dpp v214, v208, v208 row_mirror row_mask:0xf bank_mask:0x1
	v_add_f32_dpp v209, v209, v209 row_mirror row_mask:0xf bank_mask:0xf bound_ctrl:1
	v_add_f32_e32 v208, v206, v207
	v_fma_f32 v210, -v196, v209, v106
	s_waitcnt lgkmcnt(1)
	v_pk_mul_f32 v[206:207], v[80:81], v[104:105]
	v_mul_f32_e32 v212, v197, v210
	v_pk_fma_f32 v[206:207], v[82:83], v[102:103], v[206:207]
	v_pk_fma_f32 v[104:105], v[178:179], v[212:213], v[158:159] op_sel_hi:[1,0,1]
	v_pk_fma_f32 v[102:103], v[180:181], v[212:213], v[168:169] op_sel_hi:[1,0,1]
	v_pk_mul_f32 v[154:155], v[184:185], v[104:105]
	ds_read_b32 v107, v218 offset:7936
	v_pk_fma_f32 v[154:155], v[186:187], v[102:103], v[154:155]
	ds_read_b128 v[84:87], v217 offset:6144
	v_add_f32_e32 v209, v154, v155
	ds_read_b128 v[92:95], v217 offset:8448
	v_add_f32_dpp v182, v182, v182 quad_perm:[1,0,3,2] row_mask:0xf bank_mask:0xf bound_ctrl:1
	v_add_f32_dpp v209, v209, v209 quad_perm:[1,0,3,2] row_mask:0xf bank_mask:0xf bound_ctrl:1
	s_waitcnt lgkmcnt(3)
	v_pk_mul_f32 v[158:159], v[104:105], v[200:201] op_sel_hi:[1,0]
	v_add_f32_dpp v182, v182, v182 quad_perm:[2,3,0,1] row_mask:0xf bank_mask:0xf bound_ctrl:1
	v_add_f32_dpp v209, v209, v209 quad_perm:[2,3,0,1] row_mask:0xf bank_mask:0xf bound_ctrl:1
	v_pk_mul_f32 v[168:169], v[102:103], v[200:201] op_sel_hi:[1,0]
	v_add_f32_dpp v182, v182, v182 row_half_mirror row_mask:0xf bank_mask:0xf bound_ctrl:1
	v_add_f32_dpp v209, v209, v209 row_half_mirror row_mask:0xf bank_mask:0xf bound_ctrl:1
	ds_read_b128 v[188:191], v219 offset:36992
	v_add_f32_dpp v215, v182, v182 row_mirror row_mask:0xf bank_mask:0x1
	v_add_f32_dpp v209, v209, v209 row_mirror row_mask:0xf bank_mask:0xf bound_ctrl:1
	v_add_f32_e32 v182, v204, v205
	s_waitcnt lgkmcnt(1)
	v_fma_f32 v210, -v200, v209, v107
	v_pk_mul_f32 v[204:205], v[84:85], v[104:105]
	v_mul_f32_e32 v212, v201, v210
	v_pk_fma_f32 v[204:205], v[86:87], v[102:103], v[204:205]
	v_pk_fma_f32 v[104:105], v[184:185], v[212:213], v[158:159] op_sel_hi:[1,0,1]
	v_pk_fma_f32 v[102:103], v[186:187], v[212:213], v[168:169] op_sel_hi:[1,0,1]
	v_pk_mul_f32 v[154:155], v[92:93], v[104:105]
	ds_read_b32 v0, v218 offset:8960
	v_pk_fma_f32 v[154:155], v[94:95], v[102:103], v[154:155]
	ds_read_b128 v[88:91], v217 offset:7168
	v_add_f32_e32 v209, v154, v155
	ds_read_b128 v[174:177], v217 offset:9472
	v_add_f32_dpp v208, v208, v208 quad_perm:[1,0,3,2] row_mask:0xf bank_mask:0xf bound_ctrl:1
	v_add_f32_dpp v209, v209, v209 quad_perm:[1,0,3,2] row_mask:0xf bank_mask:0xf bound_ctrl:1
	s_waitcnt lgkmcnt(3)
; template <int KG> __device__ __forceinline__ float redKG(float x) { x = red8d(x); if (KG == 16) x += dpp_rm(x); return x; }
; template <int MIX, int KPL, int KG>
; __device__ __forceinline__ float do_step(const StepIn<MIX, KPL>& s, float (&S)[KPL], const float gam) {
;   if (MIX == 0) {
;     float kS0 = 0.f, kS1 = 0.f, qS0 = 0.f, qS1 = 0.f;
; #pragma unroll
;     for (int i = 0; i < KPL; i += 2) { kS0 += s.k[i] * S[i]; kS1 += s.k[i + 1] * S[i + 1]; qS0 += s.q[i] * S[i]; qS1 += s.q[i + 1] * S[i + 1]; }
;     const float kS = redKG<KG>(kS0 + kS1), qS = redKG<KG>(qS0 + qS1);
;     const float w = s.be * (s.v - s.a * kS);
; #pragma unroll
;     for (int i = 0; i < KPL; ++i) S[i] = s.a * S[i] + s.k[i] * w;
;     return s.a * qS + s.qk * w;
; template <int MIX>
; __device__ __forceinline__ void scan_part(const Params& p, const int layer, const int smp, const int b0, const int bstep, const int bend, const int h, const int part, char* lds, const int tid) {
;     ...
;     {
;       StepIn<MIX, KPL> sa, sb;
;       float osave = 0.f;
;       load_step<MIX, KPL>(qkdv, scal, 0, kg, col, sa);
;       for (int t = 0; t < ntok; t += 2) {
;         load_step<MIX, KPL>(qkdv, scal, t + 1, kg, col, sb);
;         __builtin_amdgcn_sched_barrier(0);
;         const float oa = do_step<MIX, KPL, KG>(sa, S, gam);
;         osave = (kg == (t & (KG - 1))) ? oa : osave;
;         load_step<MIX, KPL>(qkdv, scal, min(t + 2, ntok - 1), kg, col, sa);
;         __builtin_amdgcn_sched_barrier(0);
;         const float ob = do_step<MIX, KPL, KG>(sb, S, gam);
;         osave = (kg == ((t + 1) & (KG - 1))) ? ob : osave;
;         if (((t + 2) & (KG - 1)) == 0) obuf[(t + 2 - KG + kg) * CW + col] = osave;
;       }
;       const int remn = ntok & (KG - 1);
;       if (remn != 0 && kg < remn) obuf[(ntok - remn + kg) * CW + col] = osave;
;     }
	v_pk_mul_f32 v[158:159], v[104:105], v[188:189] op_sel_hi:[1,0]
	v_add_f32_dpp v208, v208, v208 quad_perm:[2,3,0,1] row_mask:0xf bank_mask:0xf bound_ctrl:1
	v_add_f32_dpp v209, v209, v209 quad_perm:[2,3,0,1] row_mask:0xf bank_mask:0xf bound_ctrl:1
	v_pk_mul_f32 v[168:169], v[102:103], v[188:189] op_sel_hi:[1,0]
	v_add_f32_dpp v208, v208, v208 row_half_mirror row_mask:0xf bank_mask:0xf bound_ctrl:1
	v_add_f32_dpp v209, v209, v209 row_half_mirror row_mask:0xf bank_mask:0xf bound_ctrl:1
	ds_read_b128 v[192:195], v219 offset:37008
	v_add_f32_dpp v216, v208, v208 row_mirror row_mask:0xf bank_mask:0x1
	v_add_f32_dpp v209, v209, v209 row_mirror row_mask:0xf bank_mask:0xf bound_ctrl:1
	v_add_f32_e32 v208, v206, v207
	s_waitcnt lgkmcnt(1)
	v_fma_f32 v210, -v188, v209, v0
	v_pk_mul_f32 v[206:207], v[88:89], v[104:105]
	v_mul_f32_e32 v212, v189, v210
	v_pk_fma_f32 v[206:207], v[90:91], v[102:103], v[206:207]
	v_pk_fma_f32 v[104:105], v[92:93], v[212:213], v[158:159] op_sel_hi:[1,0,1]
	v_pk_fma_f32 v[102:103], v[94:95], v[212:213], v[168:169] op_sel_hi:[1,0,1]
	v_pk_mul_f32 v[154:155], v[174:175], v[104:105]
	ds_read_b32 v1, v218 offset:9984
	v_pk_fma_f32 v[154:155], v[176:177], v[102:103], v[154:155]
	ds_read_b128 v[76:79], v217 offset:8192
	v_add_f32_e32 v209, v154, v155
	ds_read_b128 v[178:181], v217 offset:10496
	v_add_f32_dpp v182, v182, v182 quad_perm:[1,0,3,2] row_mask:0xf bank_mask:0xf bound_ctrl:1
	v_add_f32_dpp v209, v209, v209 quad_perm:[1,0,3,2] row_mask:0xf bank_mask:0xf bound_ctrl:1
	s_waitcnt lgkmcnt(3)
	v_pk_mul_f32 v[158:159], v[104:105], v[192:193] op_sel_hi:[1,0]
	v_add_f32_dpp v182, v182, v182 quad_perm:[2,3,0,1] row_mask:0xf bank_mask:0xf bound_ctrl:1
	v_add_f32_dpp v209, v209, v209 quad_perm:[2,3,0,1] row_mask:0xf bank_mask:0xf bound_ctrl:1
	v_pk_mul_f32 v[168:169], v[102:103], v[192:193] op_sel_hi:[1,0]
	v_add_f32_dpp v182, v182, v182 row_half_mirror row_mask:0xf bank_mask:0xf bound_ctrl:1
	v_add_f32_dpp v209, v209, v209 row_half_mirror row_mask:0xf bank_mask:0xf bound_ctrl:1
	ds_read_b128 v[196:199], v219 offset:37024
	v_add_f32_dpp v211, v182, v182 row_mirror row_mask:0xf bank_mask:0x2
	v_add_f32_dpp v209, v209, v209 row_mirror row_mask:0xf bank_mask:0xf bound_ctrl:1
	v_add_f32_e32 v182, v204, v205
	s_waitcnt lgkmcnt(1)
	v_fma_f32 v210, -v192, v209, v1
	v_pk_mul_f32 v[204:205], v[76:77], v[104:105]
	v_mul_f32_e32 v212, v193, v210
	v_pk_fma_f32 v[204:205], v[78:79], v[102:103], v[204:205]
	v_pk_fma_f32 v[104:105], v[174:175], v[212:213], v[158:159] op_sel_hi:[1,0,1]
	v_pk_fma_f32 v[102:103], v[176:177], v[212:213], v[168:169] op_sel_hi:[1,0,1]
	v_pk_mul_f32 v[154:155], v[178:179], v[104:105]
	ds_read_b32 v106, v218 offset:11008
	v_pk_fma_f32 v[154:155], v[180:181], v[102:103], v[154:155]
	ds_read_b128 v[80:83], v217 offset:9216
	v_add_f32_e32 v209, v154, v155
	ds_read_b128 v[184:187], v217 offset:11520
	v_add_f32_dpp v208, v208, v208 quad_perm:[1,0,3,2] row_mask:0xf bank_mask:0xf bound_ctrl:1
	v_add_f32_dpp v209, v209, v209 quad_perm:[1,0,3,2] row_mask:0xf bank_mask:0xf bound_ctrl:1
	s_waitcnt lgkmcnt(3)
	v_pk_mul_f32 v[158:159], v[104:105], v[196:197] op_sel_hi:[1,0]
	v_add_f32_dpp v208, v208, v208 quad_perm:[2,3,0,1] row_mask:0xf bank_mask:0xf bound_ctrl:1
	v_add_f32_dpp v209, v209, v209 quad_perm:[2,3,0,1] row_mask:0xf bank_mask:0xf bound_ctrl:1
	v_pk_mul_f32 v[168:169], v[102:103], v[196:197] op_sel_hi:[1,0]
	v_add_f32_dpp v208, v208, v208 row_half_mirror row_mask:0xf bank_mask:0xf bound_ctrl:1
	v_add_f32_dpp v209, v209, v209 row_half_mirror row_mask:0xf bank_mask:0xf bound_ctrl:1
	ds_read_b128 v[200:203], v219 offset:37040
	v_add_f32_dpp v214, v208, v208 row_mirror row_mask:0xf bank_mask:0x2
	v_add_f32_dpp v209, v209, v209 row_mirror row_mask:0xf bank_mask:0xf bound_ctrl:1
	v_add_f32_e32 v208, v206, v207
	s_waitcnt lgkmcnt(1)
	v_fma_f32 v210, -v196, v209, v106
	v_pk_mul_f32 v[206:207], v[80:81], v[104:105]
	v_mul_f32_e32 v212, v197, v210
	v_pk_fma_f32 v[206:207], v[82:83], v[102:103], v[206:207]
	v_pk_fma_f32 v[104:105], v[178:179], v[212:213], v[158:159] op_sel_hi:[1,0,1]
	v_pk_fma_f32 v[102:103], v[180:181], v[212:213], v[168:169] op_sel_hi:[1,0,1]
	v_pk_mul_f32 v[154:155], v[184:185], v[104:105]
	ds_read_b32 v107, v218 offset:12032
	v_pk_fma_f32 v[154:155], v[186:187], v[102:103], v[154:155]
	ds_read_b128 v[84:87], v217 offset:10240
	v_add_f32_e32 v209, v154, v155
	ds_read_b128 v[92:95], v217 offset:12544
	v_add_f32_dpp v182, v182, v182 quad_perm:[1,0,3,2] row_mask:0xf bank_mask:0xf bound_ctrl:1
	v_add_f32_dpp v209, v209, v209 quad_perm:[1,0,3,2] row_mask:0xf bank_mask:0xf bound_ctrl:1
	s_waitcnt lgkmcnt(3)
	v_pk_mul_f32 v[158:159], v[104:105], v[200:201] op_sel_hi:[1,0]
	v_add_f32_dpp v182, v182, v182 quad_perm:[2,3,0,1] row_mask:0xf bank_mask:0xf bound_ctrl:1
	v_add_f32_dpp v209, v209, v209 quad_perm:[2,3,0,1] row_mask:0xf bank_mask:0xf bound_ctrl:1
	v_pk_mul_f32 v[168:169], v[102:103], v[200:201] op_sel_hi:[1,0]
	v_add_f32_dpp v182, v182, v182 row_half_mirror row_mask:0xf bank_mask:0xf bound_ctrl:1
	v_add_f32_dpp v209, v209, v209 row_half_mirror row_mask:0xf bank_mask:0xf bound_ctrl:1
	ds_read_b128 v[188:191], v219 offset:37056
	v_add_f32_dpp v215, v182, v182 row_mirror row_mask:0xf bank_mask:0x2
	v_add_f32_dpp v209, v209, v209 row_mirror row_mask:0xf bank_mask:0xf bound_ctrl:1
	v_add_f32_e32 v182, v204, v205
	s_waitcnt lgkmcnt(1)
; template <int KG> __device__ __forceinline__ float redKG(float x) { x = red8d(x); if (KG == 16) x += dpp_rm(x); return x; }
; template <int MIX, int KPL, int KG>
; __device__ __forceinline__ float do_step(const StepIn<MIX, KPL>& s, float (&S)[KPL], const float gam) {
;   if (MIX == 0) {
;     float kS0 = 0.f, kS1 = 0.f, qS0 = 0.f, qS1 = 0.f;
; #pragma unroll
;     for (int i = 0; i < KPL; i += 2) { kS0 += s.k[i] * S[i]; kS1 += s.k[i + 1] * S[i + 1]; qS0 += s.q[i] * S[i]; qS1 += s.q[i + 1] * S[i + 1]; }
;     const float kS = redKG<KG>(kS0 + kS1), qS = redKG<KG>(qS0 + qS1);
;     const float w = s.be * (s.v - s.a * kS);
; #pragma unroll
;     for (int i = 0; i < KPL; ++i) S[i] = s.a * S[i] + s.k[i] * w;
;     return s.a * qS + s.qk * w;
; template <int MIX>
; __device__ __forceinline__ void scan_part(const Params& p, const int layer, const int smp, const int b0, const int bstep, const int bend, const int h, const int part, char* lds, const int tid) {
;     ...
;     {
;       StepIn<MIX, KPL> sa, sb;
;       float osave = 0.f;
;       load_step<MIX, KPL>(qkdv, scal, 0, kg, col, sa);
;       for (int t = 0; t < ntok; t += 2) {
;         load_step<MIX, KPL>(qkdv, scal, t + 1, kg, col, sb);
;         __builtin_amdgcn_sched_barrier(0);
;         const float oa = do_step<MIX, KPL, KG>(sa, S, gam);
;         osave = (kg == (t & (KG - 1))) ? oa : osave;
;         load_step<MIX, KPL>(qkdv, scal, min(t + 2, ntok - 1), kg, col, sa);
;         __builtin_amdgcn_sched_barrier(0);
;         const float ob = do_step<MIX, KPL, KG>(sb, S, gam);
;         osave = (kg == ((t + 1) & (KG - 1))) ? ob : osave;
;         if (((t + 2) & (KG - 1)) == 0) obuf[(t + 2 - KG + kg) * CW + col] = osave;
;       }
;       const int remn = ntok & (KG - 1);
;       if (remn != 0 && kg < remn) obuf[(ntok - remn + kg) * CW + col] = osave;
;     }
	v_fma_f32 v210, -v200, v209, v107
	v_pk_mul_f32 v[204:205], v[84:85], v[104:105]
	v_mul_f32_e32 v212, v201, v210
	v_pk_fma_f32 v[204:205], v[86:87], v[102:103], v[204:205]
	v_pk_fma_f32 v[104:105], v[184:185], v[212:213], v[158:159] op_sel_hi:[1,0,1]
	v_pk_fma_f32 v[102:103], v[186:187], v[212:213], v[168:169] op_sel_hi:[1,0,1]
	v_pk_mul_f32 v[154:155], v[92:93], v[104:105]
	ds_read_b32 v0, v218 offset:13056
	v_pk_fma_f32 v[154:155], v[94:95], v[102:103], v[154:155]
	ds_read_b128 v[88:91], v217 offset:11264
	v_add_f32_e32 v209, v154, v155
	ds_read_b128 v[174:177], v217 offset:13568
	v_add_f32_dpp v208, v208, v208 quad_perm:[1,0,3,2] row_mask:0xf bank_mask:0xf bound_ctrl:1
	v_add_f32_dpp v209, v209, v209 quad_perm:[1,0,3,2] row_mask:0xf bank_mask:0xf bound_ctrl:1
	s_waitcnt lgkmcnt(3)
	v_pk_mul_f32 v[158:159], v[104:105], v[188:189] op_sel_hi:[1,0]
	v_add_f32_dpp v208, v208, v208 quad_perm:[2,3,0,1] row_mask:0xf bank_mask:0xf bound_ctrl:1
	v_add_f32_dpp v209, v209, v209 quad_perm:[2,3,0,1] row_mask:0xf bank_mask:0xf bound_ctrl:1
	v_pk_mul_f32 v[168:169], v[102:103], v[188:189] op_sel_hi:[1,0]
	v_add_f32_dpp v208, v208, v208 row_half_mirror row_mask:0xf bank_mask:0xf bound_ctrl:1
	v_add_f32_dpp v209, v209, v209 row_half_mirror row_mask:0xf bank_mask:0xf bound_ctrl:1
	ds_read_b128 v[192:195], v219 offset:37072
	v_add_f32_dpp v216, v208, v208 row_mirror row_mask:0xf bank_mask:0x2
	v_add_f32_dpp v209, v209, v209 row_mirror row_mask:0xf bank_mask:0xf bound_ctrl:1
	v_add_f32_e32 v208, v206, v207
	s_waitcnt lgkmcnt(1)
	v_fma_f32 v210, -v188, v209, v0
	v_pk_mul_f32 v[206:207], v[88:89], v[104:105]
	v_mul_f32_e32 v212, v189, v210
	v_pk_fma_f32 v[206:207], v[90:91], v[102:103], v[206:207]
	v_pk_fma_f32 v[104:105], v[92:93], v[212:213], v[158:159] op_sel_hi:[1,0,1]
	v_pk_fma_f32 v[102:103], v[94:95], v[212:213], v[168:169] op_sel_hi:[1,0,1]
	v_pk_mul_f32 v[154:155], v[174:175], v[104:105]
	ds_read_b32 v1, v218 offset:14080
	v_pk_fma_f32 v[154:155], v[176:177], v[102:103], v[154:155]
	ds_read_b128 v[76:79], v217 offset:12288
	v_add_f32_e32 v209, v154, v155
	ds_read_b128 v[178:181], v217 offset:14592
	v_add_f32_dpp v182, v182, v182 quad_perm:[1,0,3,2] row_mask:0xf bank_mask:0xf bound_ctrl:1
	v_add_f32_dpp v209, v209, v209 quad_perm:[1,0,3,2] row_mask:0xf bank_mask:0xf bound_ctrl:1
	s_waitcnt lgkmcnt(3)
	v_pk_mul_f32 v[158:159], v[104:105], v[192:193] op_sel_hi:[1,0]
	v_add_f32_dpp v182, v182, v182 quad_perm:[2,3,0,1] row_mask:0xf bank_mask:0xf bound_ctrl:1
	v_add_f32_dpp v209, v209, v209 quad_perm:[2,3,0,1] row_mask:0xf bank_mask:0xf bound_ctrl:1
	v_pk_mul_f32 v[168:169], v[102:103], v[192:193] op_sel_hi:[1,0]
	v_add_f32_dpp v182, v182, v182 row_half_mirror row_mask:0xf bank_mask:0xf bound_ctrl:1
	v_add_f32_dpp v209, v209, v209 row_half_mirror row_mask:0xf bank_mask:0xf bound_ctrl:1
	ds_read_b128 v[196:199], v219 offset:37088
	v_add_f32_dpp v211, v182, v182 row_mirror row_mask:0xf bank_mask:0x4
	v_add_f32_dpp v209, v209, v209 row_mirror row_mask:0xf bank_mask:0xf bound_ctrl:1
	v_add_f32_e32 v182, v204, v205
	s_waitcnt lgkmcnt(1)
	v_fma_f32 v210, -v192, v209, v1
	v_pk_mul_f32 v[204:205], v[76:77], v[104:105]
	v_mul_f32_e32 v212, v193, v210
	v_pk_fma_f32 v[204:205], v[78:79], v[102:103], v[204:205]
	v_pk_fma_f32 v[104:105], v[174:175], v[212:213], v[158:159] op_sel_hi:[1,0,1]
	v_pk_fma_f32 v[102:103], v[176:177], v[212:213], v[168:169] op_sel_hi:[1,0,1]
	v_pk_mul_f32 v[154:155], v[178:179], v[104:105]
	ds_read_b32 v106, v218 offset:15104
	v_pk_fma_f32 v[154:155], v[180:181], v[102:103], v[154:155]
	v_add_f32_dpp v208, v208, v208 quad_perm:[1,0,3,2] row_mask:0xf bank_mask:0xf bound_ctrl:1
	ds_read_b128 v[80:83], v217 offset:13312
	v_add_f32_e32 v209, v154, v155
	ds_read_b128 v[184:187], v217 offset:15616
	v_add_f32_dpp v208, v208, v208 quad_perm:[2,3,0,1] row_mask:0xf bank_mask:0xf bound_ctrl:1
	v_add_f32_dpp v209, v209, v209 quad_perm:[1,0,3,2] row_mask:0xf bank_mask:0xf bound_ctrl:1
	v_add_f32_dpp v182, v182, v182 quad_perm:[1,0,3,2] row_mask:0xf bank_mask:0xf bound_ctrl:1
	v_add_f32_dpp v208, v208, v208 row_half_mirror row_mask:0xf bank_mask:0xf bound_ctrl:1
	v_add_f32_dpp v209, v209, v209 quad_perm:[2,3,0,1] row_mask:0xf bank_mask:0xf bound_ctrl:1
	s_waitcnt lgkmcnt(3)
	v_pk_mul_f32 v[158:159], v[104:105], v[196:197] op_sel_hi:[1,0]
	v_add_f32_dpp v214, v208, v208 row_mirror row_mask:0xf bank_mask:0x4
	v_add_f32_dpp v209, v209, v209 row_half_mirror row_mask:0xf bank_mask:0xf bound_ctrl:1
	v_add_f32_e32 v208, v206, v207
	v_pk_mul_f32 v[168:169], v[102:103], v[196:197] op_sel_hi:[1,0]
	v_add_f32_dpp v209, v209, v209 row_mirror row_mask:0xf bank_mask:0xf bound_ctrl:1
	v_add_f32_dpp v208, v208, v208 quad_perm:[1,0,3,2] row_mask:0xf bank_mask:0xf bound_ctrl:1
	s_waitcnt lgkmcnt(0)
; template <int KG> __device__ __forceinline__ float redKG(float x) { x = red8d(x); if (KG == 16) x += dpp_rm(x); return x; }
; template <int MIX, int KPL, int KG>
; __device__ __forceinline__ float do_step(const StepIn<MIX, KPL>& s, float (&S)[KPL], const float gam) {
;   if (MIX == 0) {
;     float kS0 = 0.f, kS1 = 0.f, qS0 = 0.f, qS1 = 0.f;
; #pragma unroll
;     for (int i = 0; i < KPL; i += 2) { kS0 += s.k[i] * S[i]; kS1 += s.k[i + 1] * S[i + 1]; qS0 += s.q[i] * S[i]; qS1 += s.q[i + 1] * S[i + 1]; }
;     const float kS = redKG<KG>(kS0 + kS1), qS = redKG<KG>(qS0 + qS1);
;     const float w = s.be * (s.v - s.a * kS);
; #pragma unroll
;     for (int i = 0; i < KPL; ++i) S[i] = s.a * S[i] + s.k[i] * w;
;     return s.a * qS + s.qk * w;
; template <int MIX>
; __device__ __forceinline__ void scan_part(const Params& p, const int layer, const int smp, const int b0, const int bstep, const int bend, const int h, const int part, char* lds, const int tid) {
;     ...
;     {
;       StepIn<MIX, KPL> sa, sb;
;       float osave = 0.f;
;       load_step<MIX, KPL>(qkdv, scal, 0, kg, col, sa);
;       for (int t = 0; t < ntok; t += 2) {
;         load_step<MIX, KPL>(qkdv, scal, t + 1, kg, col, sb);
;         __builtin_amdgcn_sched_barrier(0);
;         const float oa = do_step<MIX, KPL, KG>(sa, S, gam);
;         osave = (kg == (t & (KG - 1))) ? oa : osave;
;         load_step<MIX, KPL>(qkdv, scal, min(t + 2, ntok - 1), kg, col, sa);
;         __builtin_amdgcn_sched_barrier(0);
;         const float ob = do_step<MIX, KPL, KG>(sb, S, gam);
;         osave = (kg == ((t + 1) & (KG - 1))) ? ob : osave;
;         if (((t + 2) & (KG - 1)) == 0) obuf[(t + 2 - KG + kg) * CW + col] = osave;
;       }
;       const int remn = ntok & (KG - 1);
;       if (remn != 0 && kg < remn) obuf[(ntok - remn + kg) * CW + col] = osave;
;     }
	v_fma_f32 v210, -v196, v209, v106
	v_pk_mul_f32 v[206:207], v[80:81], v[104:105]
	v_mul_f32_e32 v212, v197, v210
	v_pk_fma_f32 v[206:207], v[82:83], v[102:103], v[206:207]
	v_pk_fma_f32 v[104:105], v[178:179], v[212:213], v[158:159] op_sel_hi:[1,0,1]
	v_add_f32_dpp v182, v182, v182 quad_perm:[2,3,0,1] row_mask:0xf bank_mask:0xf bound_ctrl:1
	v_add_f32_dpp v208, v208, v208 quad_perm:[2,3,0,1] row_mask:0xf bank_mask:0xf bound_ctrl:1
	v_pk_fma_f32 v[102:103], v[180:181], v[212:213], v[168:169] op_sel_hi:[1,0,1]
	v_pk_mul_f32 v[154:155], v[184:185], v[104:105]
	ds_read_b128 v[200:203], v219 offset:37104
	ds_read_b32 v107, v218 offset:16128
	v_pk_fma_f32 v[154:155], v[186:187], v[102:103], v[154:155]
	ds_read_b128 v[84:87], v217 offset:14336
	v_add_f32_e32 v209, v154, v155
	v_add_f32_dpp v182, v182, v182 row_half_mirror row_mask:0xf bank_mask:0xf bound_ctrl:1
	v_add_f32_dpp v208, v208, v208 row_half_mirror row_mask:0xf bank_mask:0xf bound_ctrl:1
	ds_read_b128 v[88:91], v217 offset:15360
	v_add_f32_dpp v209, v209, v209 quad_perm:[1,0,3,2] row_mask:0xf bank_mask:0xf bound_ctrl:1
	v_add_f32_dpp v215, v182, v182 row_mirror row_mask:0xf bank_mask:0x4
	v_add_f32_dpp v216, v208, v208 row_mirror row_mask:0xf bank_mask:0x4
	v_add_f32_e32 v182, v204, v205
	v_add_f32_e32 v208, v206, v207
	v_add_f32_dpp v209, v209, v209 quad_perm:[2,3,0,1] row_mask:0xf bank_mask:0xf bound_ctrl:1
	v_add_f32_dpp v182, v182, v182 quad_perm:[1,0,3,2] row_mask:0xf bank_mask:0xf bound_ctrl:1
	v_add_f32_dpp v208, v208, v208 quad_perm:[1,0,3,2] row_mask:0xf bank_mask:0xf bound_ctrl:1
	v_add_f32_dpp v209, v209, v209 row_half_mirror row_mask:0xf bank_mask:0xf bound_ctrl:1
	v_add_f32_dpp v182, v182, v182 quad_perm:[2,3,0,1] row_mask:0xf bank_mask:0xf bound_ctrl:1
	v_add_f32_dpp v208, v208, v208 quad_perm:[2,3,0,1] row_mask:0xf bank_mask:0xf bound_ctrl:1
	v_add_f32_dpp v209, v209, v209 row_mirror row_mask:0xf bank_mask:0xf bound_ctrl:1
	s_waitcnt lgkmcnt(0)
	v_fma_f32 v210, -v200, v209, v107
	v_add_f32_dpp v182, v182, v182 row_half_mirror row_mask:0xf bank_mask:0xf bound_ctrl:1
	v_add_f32_dpp v208, v208, v208 row_half_mirror row_mask:0xf bank_mask:0xf bound_ctrl:1
	v_pk_mul_f32 v[204:205], v[84:85], v[104:105]
	v_pk_mul_f32 v[158:159], v[104:105], v[200:201] op_sel_hi:[1,0]
	v_mul_f32_e32 v212, v201, v210
	v_pk_fma_f32 v[204:205], v[86:87], v[102:103], v[204:205]
	v_pk_mul_f32 v[168:169], v[102:103], v[200:201] op_sel_hi:[1,0]
	v_pk_fma_f32 v[104:105], v[184:185], v[212:213], v[158:159] op_sel_hi:[1,0,1]
	v_pk_fma_f32 v[102:103], v[186:187], v[212:213], v[168:169] op_sel_hi:[1,0,1]
	v_pk_mul_f32 v[206:207], v[88:89], v[104:105]
	v_add_f32_dpp v211, v182, v182 row_mirror row_mask:0xf bank_mask:0x8
	v_add_f32_dpp v214, v208, v208 row_mirror row_mask:0xf bank_mask:0x8
	v_pk_fma_f32 v[206:207], v[90:91], v[102:103], v[206:207]
	v_add_f32_e32 v182, v204, v205
	v_add_f32_e32 v208, v206, v207
	ds_read_b128 v[92:95], v217 offset:16640
	v_add_f32_dpp v182, v182, v182 quad_perm:[1,0,3,2] row_mask:0xf bank_mask:0xf bound_ctrl:1
	v_add_f32_dpp v208, v208, v208 quad_perm:[1,0,3,2] row_mask:0xf bank_mask:0xf bound_ctrl:1
	ds_read_b128 v[188:191], v219 offset:37120
	v_add_f32_dpp v182, v182, v182 quad_perm:[2,3,0,1] row_mask:0xf bank_mask:0xf bound_ctrl:1
	v_add_f32_dpp v208, v208, v208 quad_perm:[2,3,0,1] row_mask:0xf bank_mask:0xf bound_ctrl:1
	ds_read_b32 v0, v218 offset:17152
	v_add_f32_dpp v182, v182, v182 row_half_mirror row_mask:0xf bank_mask:0xf bound_ctrl:1
	v_add_f32_dpp v208, v208, v208 row_half_mirror row_mask:0xf bank_mask:0xf bound_ctrl:1
	ds_read_b128 v[76:79], v217 offset:16384
	v_add_f32_dpp v215, v182, v182 row_mirror row_mask:0xf bank_mask:0x8
	v_add_f32_dpp v216, v208, v208 row_mirror row_mask:0xf bank_mask:0x8
	ds_read_b128 v[174:177], v217 offset:17664
	ds_read_b128 v[192:195], v219 offset:37136
	ds_read_b32 v1, v218 offset:18176
	ds_read_b128 v[80:83], v217 offset:17408
	ds_write_b32 v220, v211 offset:32768
	ds_write_b32 v220, v214 offset:32832
	ds_write_b32 v220, v215 offset:32896
	ds_write_b32 v220, v216 offset:32960
	v_add_u32_e32 v217, 0x4000, v217
	v_add_u32_e32 v218, 0x4000, v218
	v_add_u32_e32 v219, 0x100, v219
	v_add_u32_e32 v220, 0x400, v220
	s_sub_i32 s50, s50, 1
	s_cmp_lg_u32 s50, 0
	s_cbranch_scc1 .Lscan0p_blk
